# rotate K-loop back edge: pointer-select scalar block runs before the iteration's final barrier
# baseline (speedup 1.0000x reference)
; #define PG8_STAGE(bufoff, gbase, voff) do { _Pragma("unroll") for (int _i = 0; _i < 2; ++_i) \
;         __builtin_amdgcn_global_load_lds((const unsigned*)((const char*)(gbase) + (voff)[_i]), (PG8_LAS unsigned*)(lds + (bufoff) + ldsw + _i * 8192), 16, 0, 0); } while (0)
; #define PG8_LDA(dst, b, h) do { _Pragma("unroll") for (int m = 0; m < 4; ++m) _Pragma("unroll") for (int k = 0; k < 2; ++k) dst[m][k] = *(const PG8_LAS bf16x8*)(lds + PG8_SA(b, h) + aoff + m * 2048 + k * 1024); } while (0)
; #define PG8_LDB(dst, b, h) do { _Pragma("unroll") for (int n = 0; n < 2; ++n) _Pragma("unroll") for (int k = 0; k < 2; ++k) dst[n][k] = *(const PG8_LAS bf16x8*)(lds + PG8_SB(b, h) + boff + n * 2048 + k * 1024); } while (0)
; #define PG8_MMA(ai, bj, At, Bt) do { __builtin_amdgcn_s_setprio(1); _Pragma("unroll") for (int m = 0; m < 4; ++m) _Pragma("unroll") for (int n = 0; n < 2; ++n) _Pragma("unroll") for (int k = 0; k < 2; ++k) \
;         acc[ai][bj][m][n] = __builtin_amdgcn_mfma_f32_16x16x32_bf16(Bt[n][k], At[m][k], acc[ai][bj][m][n], 0, 0, 0); __builtin_amdgcn_s_setprio(0); } while (0)
; #define PG8_WAIT_V(n) asm volatile("s_waitcnt vmcnt(" #n ")" ::: "memory")
; #define PG8_WAIT_L(n) asm volatile("s_waitcnt lgkmcnt(" #n ")" ::: "memory")
; #define PG8_BAR __builtin_amdgcn_s_barrier()
; #define PG8_SCHED __builtin_amdgcn_sched_barrier(0)
; template <class Epi, class Sched, bool ALIGN_EPI = false, bool SP2 = false>
; __device__ __forceinline__ void gemm_phase(PG8_LAS unsigned char* lds, const Gemm g, const Sched& S, const Epi& E) {
;     ...
;             PG8_LDB(B0, 0, 0); PG8_LDB(B1, 0, 1); PG8_SCHED; PG8_LDA(At, 0, 0); PG8_STAGE(PG8_SA(1, 1), a1 + hstep, voffA);
;             PG8_WAIT_V(8); PG8_WAIT_L(0); PG8_BAR; PG8_MMA(0, 0, At, B0); PG8_MMA(0, 1, At, B1); PG8_BAR; PG8_SCHED;
;             PG8_LDA(At, 0, 1); PG8_STAGE(PG8_SB(0, 0), b2, voffB); PG8_STAGE(PG8_SB(0, 1), b2 + hstep, voffB); PG8_STAGE(PG8_SA(0, 0), a2, voffA);
.Lrot_body_g1:
	v_add_u32_e32 v140, s67, v183
	v_add_u32_e32 v166, s10, v183
	ds_read_b128 v[128:131], v140
	ds_read_b128 v[132:135], v140 offset:1024
	ds_read_b128 v[136:139], v140 offset:2048
	ds_read_b128 v[140:143], v140 offset:3072
	ds_read_b128 v[144:147], v166
	ds_read_b128 v[148:151], v166 offset:1024
	ds_read_b128 v[152:155], v166 offset:2048
	ds_read_b128 v[166:169], v166 offset:3072
	v_lshl_add_u64 v[190:191], s[44:45], 0, v[162:163]
	s_add_i32 m0, s23, 0xc000
	ds_read_b128 v[170:173], v185
	ds_read_b128 v[174:177], v185 offset:1024
	ds_read_b128 v[178:181], v185 offset:2048
	ds_read_b128 v[186:189], v185 offset:3072
	ds_read_b128 v[194:197], v185 offset:4096
	ds_read_b128 v[198:201], v185 offset:5120
	ds_read_b128 v[202:205], v185 offset:6144
	ds_read_b128 v[206:209], v185 offset:7168
	global_load_lds_dwordx4 v[190:191], off
	v_lshl_add_u64 v[190:191], s[44:45], 0, v[164:165]
	s_add_i32 m0, s23, 0xe000
	s_nop 0
	global_load_lds_dwordx4 v[190:191], off
	s_waitcnt vmcnt(8)
	s_waitcnt lgkmcnt(0)
	s_barrier
	s_setprio 1
	s_waitcnt lgkmcnt(0)
	v_mfma_f32_16x16x32_bf16 v[124:127], v[128:131], v[170:173], v[124:127]
	v_mfma_f32_16x16x32_bf16 v[120:123], v[136:139], v[170:173], v[120:123]
	v_mfma_f32_16x16x32_bf16 v[108:111], v[128:131], v[178:181], v[108:111]
	v_mfma_f32_16x16x32_bf16 v[104:107], v[136:139], v[178:181], v[104:107]
	v_mfma_f32_16x16x32_bf16 v[92:95], v[128:131], v[194:197], v[92:95]
	v_mfma_f32_16x16x32_bf16 v[88:91], v[136:139], v[194:197], v[88:91]
	v_mfma_f32_16x16x32_bf16 v[76:79], v[128:131], v[202:205], v[76:79]
	v_mfma_f32_16x16x32_bf16 v[72:75], v[136:139], v[202:205], v[72:75]
	v_mfma_f32_16x16x32_bf16 v[124:127], v[132:135], v[174:177], v[124:127]
	v_mfma_f32_16x16x32_bf16 v[120:123], v[140:143], v[174:177], v[120:123]
	v_mfma_f32_16x16x32_bf16 v[108:111], v[132:135], v[186:189], v[108:111]
	v_mfma_f32_16x16x32_bf16 v[104:107], v[140:143], v[186:189], v[104:107]
	v_mfma_f32_16x16x32_bf16 v[92:95], v[132:135], v[198:201], v[92:95]
	v_mfma_f32_16x16x32_bf16 v[88:91], v[140:143], v[198:201], v[88:91]
	v_mfma_f32_16x16x32_bf16 v[76:79], v[132:135], v[206:209], v[76:79]
	v_mfma_f32_16x16x32_bf16 v[72:75], v[140:143], v[206:209], v[72:75]
	s_setprio 0
	s_setprio 1
	v_mfma_f32_16x16x32_bf16 v[116:119], v[144:147], v[170:173], v[116:119]
	v_mfma_f32_16x16x32_bf16 v[112:115], v[152:155], v[170:173], v[112:115]
	v_mfma_f32_16x16x32_bf16 v[100:103], v[144:147], v[178:181], v[100:103]
	v_mfma_f32_16x16x32_bf16 v[96:99], v[152:155], v[178:181], v[96:99]
	v_mfma_f32_16x16x32_bf16 v[84:87], v[144:147], v[194:197], v[84:87]
	v_mfma_f32_16x16x32_bf16 v[80:83], v[152:155], v[194:197], v[80:83]
	v_mfma_f32_16x16x32_bf16 v[68:71], v[144:147], v[202:205], v[68:71]
	v_mfma_f32_16x16x32_bf16 v[64:67], v[152:155], v[202:205], v[64:67]
	v_mfma_f32_16x16x32_bf16 v[116:119], v[148:151], v[174:177], v[116:119]
	v_mfma_f32_16x16x32_bf16 v[112:115], v[166:169], v[174:177], v[112:115]
	v_mfma_f32_16x16x32_bf16 v[100:103], v[148:151], v[186:189], v[100:103]
	v_mfma_f32_16x16x32_bf16 v[96:99], v[166:169], v[186:189], v[96:99]
	v_mfma_f32_16x16x32_bf16 v[84:87], v[148:151], v[198:201], v[84:87]
	v_mfma_f32_16x16x32_bf16 v[80:83], v[166:169], v[198:201], v[80:83]
	v_mfma_f32_16x16x32_bf16 v[68:71], v[148:151], v[206:209], v[68:71]
	v_mfma_f32_16x16x32_bf16 v[64:67], v[166:169], v[206:209], v[64:67]
	s_setprio 0
	s_barrier
	s_add_i32 s11, s67, s22
	v_lshl_add_u64 v[190:191], s[78:79], 0, v[192:193]
	s_mov_b32 m0, s11
	ds_read_b128 v[170:173], v185 offset:16384
	ds_read_b128 v[174:177], v185 offset:17408
	ds_read_b128 v[178:181], v185 offset:18432
	ds_read_b128 v[186:189], v185 offset:19456
	ds_read_b128 v[194:197], v185 offset:20480
	ds_read_b128 v[198:201], v185 offset:21504
	ds_read_b128 v[202:205], v185 offset:22528
	ds_read_b128 v[206:209], v185 offset:23552
	global_load_lds_dwordx4 v[190:191], off
	s_add_i32 m0, s11, 0x2000
	v_lshl_add_u64 v[210:211], s[78:79], 0, v[160:161]
	s_add_u32 s78, s78, s52
	s_addc_u32 s79, s79, 0
	s_add_i32 s10, s10, s22
	global_load_lds_dwordx4 v[210:211], off
	v_lshl_add_u64 v[212:213], s[78:79], 0, v[192:193]
	s_mov_b32 m0, s10
	v_lshl_add_u64 v[214:215], s[78:79], 0, v[160:161]
	global_load_lds_dwordx4 v[212:213], off
	s_add_i32 m0, s10, 0x2000
	v_lshl_add_u64 v[216:217], s[46:47], 0, v[156:157]
	global_load_lds_dwordx4 v[214:215], off
	s_mov_b32 m0, s23
	v_lshl_add_u64 v[218:219], s[46:47], 0, v[158:159]
	global_load_lds_dwordx4 v[216:217], off
	s_mov_b32 m0, s51
	s_nop 0
	global_load_lds_dwordx4 v[218:219], off
	s_waitcnt vmcnt(8)
	s_waitcnt lgkmcnt(0)
	s_barrier
; #define PG8_STAGE(bufoff, gbase, voff) do { _Pragma("unroll") for (int _i = 0; _i < 2; ++_i) \
;         __builtin_amdgcn_global_load_lds((const unsigned*)((const char*)(gbase) + (voff)[_i]), (PG8_LAS unsigned*)(lds + (bufoff) + ldsw + _i * 8192), 16, 0, 0); } while (0)
; #define PG8_LDA(dst, b, h) do { _Pragma("unroll") for (int m = 0; m < 4; ++m) _Pragma("unroll") for (int k = 0; k < 2; ++k) dst[m][k] = *(const PG8_LAS bf16x8*)(lds + PG8_SA(b, h) + aoff + m * 2048 + k * 1024); } while (0)
; #define PG8_LDB(dst, b, h) do { _Pragma("unroll") for (int n = 0; n < 2; ++n) _Pragma("unroll") for (int k = 0; k < 2; ++k) dst[n][k] = *(const PG8_LAS bf16x8*)(lds + PG8_SB(b, h) + boff + n * 2048 + k * 1024); } while (0)
; #define PG8_MMA(ai, bj, At, Bt) do { __builtin_amdgcn_s_setprio(1); _Pragma("unroll") for (int m = 0; m < 4; ++m) _Pragma("unroll") for (int n = 0; n < 2; ++n) _Pragma("unroll") for (int k = 0; k < 2; ++k) \
;         acc[ai][bj][m][n] = __builtin_amdgcn_mfma_f32_16x16x32_bf16(Bt[n][k], At[m][k], acc[ai][bj][m][n], 0, 0, 0); __builtin_amdgcn_s_setprio(0); } while (0)
; #define PG8_WAIT_V(n) asm volatile("s_waitcnt vmcnt(" #n ")" ::: "memory")
; #define PG8_WAIT_L(n) asm volatile("s_waitcnt lgkmcnt(" #n ")" ::: "memory")
; #define PG8_BAR __builtin_amdgcn_s_barrier()
; #define PG8_SCHED __builtin_amdgcn_sched_barrier(0)
; template <class Epi, class Sched, bool ALIGN_EPI = false, bool SP2 = false>
; __device__ __forceinline__ void gemm_phase(PG8_LAS unsigned char* lds, const Gemm g, const Sched& S, const Epi& E) {
;     ...
;             PG8_WAIT_V(8); PG8_WAIT_L(0); PG8_BAR; PG8_MMA(1, 0, At, B0); PG8_MMA(1, 1, At, B1); PG8_BAR; PG8_SCHED;
;             PG8_LDB(B0, 1, 0); PG8_LDB(B1, 1, 1); PG8_SCHED; PG8_LDA(At, 1, 0); PG8_STAGE(PG8_SA(0, 1), a2 + hstep, voffA);
;             PG8_WAIT_V(8); PG8_WAIT_L(0); PG8_BAR; PG8_MMA(0, 0, At, B0); PG8_MMA(0, 1, At, B1); PG8_BAR; PG8_SCHED;
	s_setprio 1
	s_waitcnt lgkmcnt(0)
	v_mfma_f32_16x16x32_bf16 v[60:63], v[128:131], v[170:173], v[60:63]
	v_mfma_f32_16x16x32_bf16 v[56:59], v[136:139], v[170:173], v[56:59]
	v_mfma_f32_16x16x32_bf16 v[44:47], v[128:131], v[178:181], v[44:47]
	v_mfma_f32_16x16x32_bf16 v[40:43], v[136:139], v[178:181], v[40:43]
	v_mfma_f32_16x16x32_bf16 v[28:31], v[128:131], v[194:197], v[28:31]
	v_mfma_f32_16x16x32_bf16 v[24:27], v[136:139], v[194:197], v[24:27]
	v_mfma_f32_16x16x32_bf16 v[12:15], v[128:131], v[202:205], v[12:15]
	v_mfma_f32_16x16x32_bf16 v[8:11], v[136:139], v[202:205], v[8:11]
	v_mfma_f32_16x16x32_bf16 v[60:63], v[132:135], v[174:177], v[60:63]
	v_mfma_f32_16x16x32_bf16 v[56:59], v[140:143], v[174:177], v[56:59]
	v_mfma_f32_16x16x32_bf16 v[44:47], v[132:135], v[186:189], v[44:47]
	v_mfma_f32_16x16x32_bf16 v[40:43], v[140:143], v[186:189], v[40:43]
	v_mfma_f32_16x16x32_bf16 v[28:31], v[132:135], v[198:201], v[28:31]
	v_mfma_f32_16x16x32_bf16 v[24:27], v[140:143], v[198:201], v[24:27]
	v_mfma_f32_16x16x32_bf16 v[12:15], v[132:135], v[206:209], v[12:15]
	v_mfma_f32_16x16x32_bf16 v[8:11], v[140:143], v[206:209], v[8:11]
	s_setprio 0
	s_setprio 1
	v_mfma_f32_16x16x32_bf16 v[52:55], v[144:147], v[170:173], v[52:55]
	v_mfma_f32_16x16x32_bf16 v[48:51], v[152:155], v[170:173], v[48:51]
	v_mfma_f32_16x16x32_bf16 v[36:39], v[144:147], v[178:181], v[36:39]
	v_mfma_f32_16x16x32_bf16 v[32:35], v[152:155], v[178:181], v[32:35]
	v_mfma_f32_16x16x32_bf16 v[20:23], v[144:147], v[194:197], v[20:23]
	v_mfma_f32_16x16x32_bf16 v[16:19], v[152:155], v[194:197], v[16:19]
	v_mfma_f32_16x16x32_bf16 v[4:7], v[144:147], v[202:205], v[4:7]
	v_mfma_f32_16x16x32_bf16 v[0:3], v[152:155], v[202:205], v[0:3]
	v_mfma_f32_16x16x32_bf16 v[52:55], v[148:151], v[174:177], v[52:55]
	v_mfma_f32_16x16x32_bf16 v[48:51], v[166:169], v[174:177], v[48:51]
	v_mfma_f32_16x16x32_bf16 v[36:39], v[148:151], v[186:189], v[36:39]
	v_mfma_f32_16x16x32_bf16 v[32:35], v[166:169], v[186:189], v[32:35]
	v_mfma_f32_16x16x32_bf16 v[20:23], v[148:151], v[198:201], v[20:23]
	v_mfma_f32_16x16x32_bf16 v[16:19], v[166:169], v[198:201], v[16:19]
	v_mfma_f32_16x16x32_bf16 v[4:7], v[148:151], v[206:209], v[4:7]
	v_mfma_f32_16x16x32_bf16 v[0:3], v[166:169], v[206:209], v[0:3]
	s_setprio 0
	s_barrier
	s_add_i32 s10, 0, 0x18000
	s_add_i32 s11, 0, 0x1c000
	v_add_u32_e32 v140, s10, v183
	v_add_u32_e32 v166, s11, v183
	ds_read_b128 v[128:131], v140
	ds_read_b128 v[132:135], v140 offset:1024
	ds_read_b128 v[136:139], v140 offset:2048
	ds_read_b128 v[140:143], v140 offset:3072
	ds_read_b128 v[144:147], v166
	ds_read_b128 v[148:151], v166 offset:1024
	ds_read_b128 v[152:155], v166 offset:2048
	ds_read_b128 v[166:169], v166 offset:3072
	s_add_u32 s46, s46, s52
	s_addc_u32 s47, s47, 0
	s_mov_b32 m0, s68
	v_lshl_add_u64 v[220:221], s[46:47], 0, v[156:157]
	ds_read_b128 v[170:173], v185 offset:32768
	ds_read_b128 v[174:177], v185 offset:33792
	ds_read_b128 v[178:181], v185 offset:34816
	ds_read_b128 v[186:189], v185 offset:35840
	ds_read_b128 v[194:197], v185 offset:36864
	ds_read_b128 v[198:201], v185 offset:37888
	ds_read_b128 v[202:205], v185 offset:38912
	ds_read_b128 v[206:209], v185 offset:39936
	global_load_lds_dwordx4 v[220:221], off
	v_lshl_add_u64 v[220:221], s[46:47], 0, v[158:159]
	s_mov_b32 m0, s69
	s_nop 0
	global_load_lds_dwordx4 v[220:221], off
	s_waitcnt vmcnt(8)
	s_waitcnt lgkmcnt(0)
	s_barrier
	s_setprio 1
	s_waitcnt lgkmcnt(0)
	v_mfma_f32_16x16x32_bf16 v[124:127], v[128:131], v[170:173], v[124:127]
	v_mfma_f32_16x16x32_bf16 v[120:123], v[136:139], v[170:173], v[120:123]
	v_mfma_f32_16x16x32_bf16 v[108:111], v[128:131], v[178:181], v[108:111]
	v_mfma_f32_16x16x32_bf16 v[104:107], v[136:139], v[178:181], v[104:107]
	v_mfma_f32_16x16x32_bf16 v[92:95], v[128:131], v[194:197], v[92:95]
	v_mfma_f32_16x16x32_bf16 v[88:91], v[136:139], v[194:197], v[88:91]
	v_mfma_f32_16x16x32_bf16 v[76:79], v[128:131], v[202:205], v[76:79]
	v_mfma_f32_16x16x32_bf16 v[72:75], v[136:139], v[202:205], v[72:75]
	v_mfma_f32_16x16x32_bf16 v[124:127], v[132:135], v[174:177], v[124:127]
	v_mfma_f32_16x16x32_bf16 v[120:123], v[140:143], v[174:177], v[120:123]
	v_mfma_f32_16x16x32_bf16 v[108:111], v[132:135], v[186:189], v[108:111]
	v_mfma_f32_16x16x32_bf16 v[104:107], v[140:143], v[186:189], v[104:107]
	v_mfma_f32_16x16x32_bf16 v[92:95], v[132:135], v[198:201], v[92:95]
	v_mfma_f32_16x16x32_bf16 v[88:91], v[140:143], v[198:201], v[88:91]
	v_mfma_f32_16x16x32_bf16 v[76:79], v[132:135], v[206:209], v[76:79]
	v_mfma_f32_16x16x32_bf16 v[72:75], v[140:143], v[206:209], v[72:75]
	s_setprio 0
	s_setprio 1
	v_mfma_f32_16x16x32_bf16 v[116:119], v[144:147], v[170:173], v[116:119]
	v_mfma_f32_16x16x32_bf16 v[112:115], v[152:155], v[170:173], v[112:115]
	v_mfma_f32_16x16x32_bf16 v[100:103], v[144:147], v[178:181], v[100:103]
	v_mfma_f32_16x16x32_bf16 v[96:99], v[152:155], v[178:181], v[96:99]
	v_mfma_f32_16x16x32_bf16 v[84:87], v[144:147], v[194:197], v[84:87]
	v_mfma_f32_16x16x32_bf16 v[80:83], v[152:155], v[194:197], v[80:83]
	v_mfma_f32_16x16x32_bf16 v[68:71], v[144:147], v[202:205], v[68:71]
	v_mfma_f32_16x16x32_bf16 v[64:67], v[152:155], v[202:205], v[64:67]
	v_mfma_f32_16x16x32_bf16 v[116:119], v[148:151], v[174:177], v[116:119]
	v_mfma_f32_16x16x32_bf16 v[112:115], v[166:169], v[174:177], v[112:115]
	v_mfma_f32_16x16x32_bf16 v[100:103], v[148:151], v[186:189], v[100:103]
	v_mfma_f32_16x16x32_bf16 v[96:99], v[166:169], v[186:189], v[96:99]
	v_mfma_f32_16x16x32_bf16 v[84:87], v[148:151], v[198:201], v[84:87]
	v_mfma_f32_16x16x32_bf16 v[80:83], v[166:169], v[198:201], v[80:83]
	v_mfma_f32_16x16x32_bf16 v[68:71], v[148:151], v[206:209], v[68:71]
	v_mfma_f32_16x16x32_bf16 v[64:67], v[166:169], v[206:209], v[64:67]
	s_setprio 0
	s_barrier
; #define PG8_STAGE(bufoff, gbase, voff) do { _Pragma("unroll") for (int _i = 0; _i < 2; ++_i) \
;         __builtin_amdgcn_global_load_lds((const unsigned*)((const char*)(gbase) + (voff)[_i]), (PG8_LAS unsigned*)(lds + (bufoff) + ldsw + _i * 8192), 16, 0, 0); } while (0)
; #define PG8_LDA(dst, b, h) do { _Pragma("unroll") for (int m = 0; m < 4; ++m) _Pragma("unroll") for (int k = 0; k < 2; ++k) dst[m][k] = *(const PG8_LAS bf16x8*)(lds + PG8_SA(b, h) + aoff + m * 2048 + k * 1024); } while (0)
; #define PG8_LDB(dst, b, h) do { _Pragma("unroll") for (int n = 0; n < 2; ++n) _Pragma("unroll") for (int k = 0; k < 2; ++k) dst[n][k] = *(const PG8_LAS bf16x8*)(lds + PG8_SB(b, h) + boff + n * 2048 + k * 1024); } while (0)
; #define PG8_BAR __builtin_amdgcn_s_barrier()
; template <class Epi, class Sched, bool ALIGN_EPI = false, bool SP2 = false>
; __device__ __forceinline__ void gemm_phase(PG8_LAS unsigned char* lds, const Gemm g, const Sched& S, const Epi& E) {
;     ...
;             const bool last = (t == nt - 2);
;             const char* a1 = cA + (size_t)(t + 1) * kstep;
;             const char* a2 = last ? nA : cA + (size_t)(t + 2) * kstep; const char* b2 = last ? nB : cB + (size_t)(t + 2) * kstep;
;             const char* a3 = a2 + kstep; const char* b3 = b2 + kstep;
;             if (last && has_next) S.a_ready(nxt);
;             if constexpr (SP2) {
;             PG8_LDB(B0, 0, 0); PG8_LDB(B1, 0, 1); PG8_SCHED; PG8_LDA(At, 0, 0); PG8_STAGE(PG8_SA(1, 1), a1 + hstep, voffA);
;             PG8_WAIT_V(8); PG8_WAIT_L(0); PG8_BAR; PG8_MMA(0, 0, At, B0); PG8_MMA(0, 1, At, B1); PG8_BAR; PG8_SCHED;
;             PG8_LDA(At, 0, 1); PG8_STAGE(PG8_SB(0, 0), b2, voffB); PG8_STAGE(PG8_SB(0, 1), b2 + hstep, voffB); PG8_STAGE(PG8_SA(0, 0), a2, voffA);
;             PG8_WAIT_V(8); PG8_WAIT_L(0); PG8_BAR; PG8_MMA(1, 0, At, B0); PG8_MMA(1, 1, At, B1); PG8_BAR; PG8_SCHED;
;             PG8_LDB(B0, 1, 0); PG8_LDB(B1, 1, 1); PG8_SCHED; PG8_LDA(At, 1, 0); PG8_STAGE(PG8_SA(0, 1), a2 + hstep, voffA);
;             PG8_WAIT_V(8); PG8_WAIT_L(0); PG8_BAR; PG8_MMA(0, 0, At, B0); PG8_MMA(0, 1, At, B1); PG8_BAR; PG8_SCHED;
;             PG8_LDA(At, 1, 1); PG8_STAGE(PG8_SB(1, 0), b3, voffB); PG8_STAGE(PG8_SB(1, 1), b3 + hstep, voffB); PG8_STAGE(PG8_SA(1, 0), a3, voffA);
;             PG8_WAIT_V(8); PG8_WAIT_L(0); PG8_BAR; PG8_MMA(1, 0, At, B0); PG8_MMA(1, 1, At, B1); PG8_BAR; PG8_SCHED;
	s_add_i32 s10, s10, s22
	v_lshl_add_u64 v[190:191], v[190:191], 0, s[36:37]
	s_mov_b32 m0, s10
	ds_read_b128 v[170:173], v185 offset:49152
	ds_read_b128 v[174:177], v185 offset:50176
	ds_read_b128 v[178:181], v185 offset:51200
	ds_read_b128 v[186:189], v185 offset:52224
	ds_read_b128 v[194:197], v185 offset:53248
	ds_read_b128 v[198:201], v185 offset:54272
	ds_read_b128 v[202:205], v185 offset:55296
	ds_read_b128 v[206:209], v185 offset:56320
	global_load_lds_dwordx4 v[190:191], off
	v_lshl_add_u64 v[190:191], v[210:211], 0, s[36:37]
	s_add_i32 m0, s10, 0x2000
	s_add_i32 s10, s11, s22
	global_load_lds_dwordx4 v[190:191], off
	v_lshl_add_u64 v[190:191], v[212:213], 0, s[36:37]
	s_mov_b32 m0, s10
	s_nop 0
	global_load_lds_dwordx4 v[190:191], off
	v_lshl_add_u64 v[190:191], v[214:215], 0, s[36:37]
	s_add_i32 m0, s10, 0x2000
	s_nop 0
	global_load_lds_dwordx4 v[190:191], off
	v_lshl_add_u64 v[190:191], v[216:217], 0, s[36:37]
	s_mov_b32 m0, s70
	s_nop 0
	global_load_lds_dwordx4 v[190:191], off
	v_lshl_add_u64 v[190:191], v[218:219], 0, s[36:37]
	s_mov_b32 m0, s71
	s_nop 0
	global_load_lds_dwordx4 v[190:191], off
	s_waitcnt vmcnt(8)
	s_waitcnt lgkmcnt(0)
	s_barrier
	s_setprio 1
	s_waitcnt lgkmcnt(0)
	v_mfma_f32_16x16x32_bf16 v[60:63], v[128:131], v[170:173], v[60:63]
	v_mfma_f32_16x16x32_bf16 v[56:59], v[136:139], v[170:173], v[56:59]
	v_mfma_f32_16x16x32_bf16 v[44:47], v[128:131], v[178:181], v[44:47]
	v_mfma_f32_16x16x32_bf16 v[40:43], v[136:139], v[178:181], v[40:43]
	v_mfma_f32_16x16x32_bf16 v[28:31], v[128:131], v[194:197], v[28:31]
	v_mfma_f32_16x16x32_bf16 v[24:27], v[136:139], v[194:197], v[24:27]
	v_mfma_f32_16x16x32_bf16 v[12:15], v[128:131], v[202:205], v[12:15]
	v_mfma_f32_16x16x32_bf16 v[8:11], v[136:139], v[202:205], v[8:11]
	v_mfma_f32_16x16x32_bf16 v[60:63], v[132:135], v[174:177], v[60:63]
	v_mfma_f32_16x16x32_bf16 v[56:59], v[140:143], v[174:177], v[56:59]
	v_mfma_f32_16x16x32_bf16 v[44:47], v[132:135], v[186:189], v[44:47]
	v_mfma_f32_16x16x32_bf16 v[40:43], v[140:143], v[186:189], v[40:43]
	v_mfma_f32_16x16x32_bf16 v[28:31], v[132:135], v[198:201], v[28:31]
	v_mfma_f32_16x16x32_bf16 v[24:27], v[140:143], v[198:201], v[24:27]
	v_mfma_f32_16x16x32_bf16 v[12:15], v[132:135], v[206:209], v[12:15]
	v_mfma_f32_16x16x32_bf16 v[8:11], v[140:143], v[206:209], v[8:11]
	s_setprio 0
	s_setprio 1
	v_mfma_f32_16x16x32_bf16 v[52:55], v[144:147], v[170:173], v[52:55]
	v_mfma_f32_16x16x32_bf16 v[48:51], v[152:155], v[170:173], v[48:51]
	v_mfma_f32_16x16x32_bf16 v[36:39], v[144:147], v[178:181], v[36:39]
	v_mfma_f32_16x16x32_bf16 v[32:35], v[152:155], v[178:181], v[32:35]
	v_mfma_f32_16x16x32_bf16 v[20:23], v[144:147], v[194:197], v[20:23]
	v_mfma_f32_16x16x32_bf16 v[16:19], v[152:155], v[194:197], v[16:19]
	v_mfma_f32_16x16x32_bf16 v[4:7], v[144:147], v[202:205], v[4:7]
	v_mfma_f32_16x16x32_bf16 v[0:3], v[152:155], v[202:205], v[0:3]
	v_mfma_f32_16x16x32_bf16 v[52:55], v[148:151], v[174:177], v[52:55]
	v_mfma_f32_16x16x32_bf16 v[48:51], v[166:169], v[174:177], v[48:51]
	v_mfma_f32_16x16x32_bf16 v[36:39], v[148:151], v[186:189], v[36:39]
	v_mfma_f32_16x16x32_bf16 v[32:35], v[166:169], v[186:189], v[32:35]
	v_mfma_f32_16x16x32_bf16 v[20:23], v[148:151], v[198:201], v[20:23]
	v_mfma_f32_16x16x32_bf16 v[16:19], v[166:169], v[198:201], v[16:19]
	v_mfma_f32_16x16x32_bf16 v[4:7], v[148:151], v[206:209], v[4:7]
	v_mfma_f32_16x16x32_bf16 v[0:3], v[166:169], v[206:209], v[0:3]
	s_setprio 0
	s_add_u32 s44, s44, 0x100
	s_addc_u32 s45, s45, 0
	s_add_u32 s19, s19, 0x100
	s_addc_u32 s20, s20, 0
	s_cmp_ge_u32 s66, s73
	s_mov_b32 s46, s66
	s_cbranch_scc1 .Lrot_exit_g1
	s_add_i32 s66, s46, 2
	s_add_u32 s10, s44, 0x80
	s_addc_u32 s11, s45, 0
	s_add_i32 s67, 0, 0x10000
	s_cmp_eq_u32 s74, s46
	s_cselect_b32 s47, s63, s11
	s_cselect_b32 s46, s62, s10
	s_cselect_b32 s79, s65, s20
	s_cselect_b32 s78, s64, s19
	s_add_i32 s10, 0, 0x14000
	s_barrier
	s_branch .Lrot_body_g1
.Lrot_exit_g1:
	s_barrier
	s_and_b64 vcc, exec, s[56:57]
	s_cbranch_vccz .LBB0_66
	s_barrier

; #define PG8_STAGE(bufoff, gbase, voff) do { _Pragma("unroll") for (int _i = 0; _i < 2; ++_i) \
;         __builtin_amdgcn_global_load_lds((const unsigned*)((const char*)(gbase) + (voff)[_i]), (PG8_LAS unsigned*)(lds + (bufoff) + ldsw + _i * 8192), 16, 0, 0); } while (0)
; #define PG8_LDA(dst, b, h) do { _Pragma("unroll") for (int m = 0; m < 4; ++m) _Pragma("unroll") for (int k = 0; k < 2; ++k) dst[m][k] = *(const PG8_LAS bf16x8*)(lds + PG8_SA(b, h) + aoff + m * 2048 + k * 1024); } while (0)
; #define PG8_LDB(dst, b, h) do { _Pragma("unroll") for (int n = 0; n < 2; ++n) _Pragma("unroll") for (int k = 0; k < 2; ++k) dst[n][k] = *(const PG8_LAS bf16x8*)(lds + PG8_SB(b, h) + boff + n * 2048 + k * 1024); } while (0)
; #define PG8_MMA(ai, bj, At, Bt) do { __builtin_amdgcn_s_setprio(1); _Pragma("unroll") for (int m = 0; m < 4; ++m) _Pragma("unroll") for (int n = 0; n < 2; ++n) _Pragma("unroll") for (int k = 0; k < 2; ++k) \
;         acc[ai][bj][m][n] = __builtin_amdgcn_mfma_f32_16x16x32_bf16(Bt[n][k], At[m][k], acc[ai][bj][m][n], 0, 0, 0); __builtin_amdgcn_s_setprio(0); } while (0)
; #define PG8_WAIT_V(n) asm volatile("s_waitcnt vmcnt(" #n ")" ::: "memory")
; #define PG8_WAIT_L(n) asm volatile("s_waitcnt lgkmcnt(" #n ")" ::: "memory")
; #define PG8_BAR __builtin_amdgcn_s_barrier()
; #define PG8_SCHED __builtin_amdgcn_sched_barrier(0)
; template <class Epi, class Sched, bool ALIGN_EPI = false, bool SP2 = false>
; __device__ __forceinline__ void gemm_phase(PG8_LAS unsigned char* lds, const Gemm g, const Sched& S, const Epi& E) {
;     ...
;             PG8_LDB(B0, 0, 0); PG8_LDB(B1, 0, 1); PG8_SCHED; PG8_LDA(At, 0, 0); PG8_STAGE(PG8_SA(1, 1), a1 + hstep, voffA);
;             PG8_WAIT_V(8); PG8_WAIT_L(0); PG8_BAR; PG8_MMA(0, 0, At, B0); PG8_MMA(0, 1, At, B1); PG8_BAR; PG8_SCHED;
;             PG8_LDA(At, 0, 1); PG8_STAGE(PG8_SB(0, 0), b2, voffB); PG8_STAGE(PG8_SB(0, 1), b2 + hstep, voffB); PG8_STAGE(PG8_SA(0, 0), a2, voffA);
.Lrot_body_g2:
	v_add_u32_e32 v140, s77, v163
	v_add_u32_e32 v162, s10, v163
	ds_read_b128 v[128:131], v140
	ds_read_b128 v[132:135], v140 offset:1024
	ds_read_b128 v[136:139], v140 offset:2048
	ds_read_b128 v[140:143], v140 offset:3072
	ds_read_b128 v[166:169], v162
	ds_read_b128 v[170:173], v162 offset:1024
	ds_read_b128 v[174:177], v162 offset:2048
	ds_read_b128 v[178:181], v162 offset:3072
	v_lshl_add_u64 v[190:191], s[56:57], 0, v[158:159]
	s_add_i32 m0, s64, 0xc000
	ds_read_b128 v[182:185], v165
	ds_read_b128 v[186:189], v165 offset:1024
	ds_read_b128 v[194:197], v165 offset:2048
	ds_read_b128 v[198:201], v165 offset:3072
	ds_read_b128 v[202:205], v165 offset:4096
	ds_read_b128 v[206:209], v165 offset:5120
	ds_read_b128 v[210:213], v165 offset:6144
	ds_read_b128 v[214:217], v165 offset:7168
	global_load_lds_dwordx4 v[190:191], off
	v_lshl_add_u64 v[190:191], s[56:57], 0, v[160:161]
	s_add_i32 m0, s64, 0xe000
	s_nop 0
	global_load_lds_dwordx4 v[190:191], off
	s_waitcnt vmcnt(8)
	s_waitcnt lgkmcnt(0)
	s_barrier
	s_setprio 1
	s_waitcnt lgkmcnt(0)
	v_mfma_f32_16x16x32_bf16 v[124:127], v[128:131], v[182:185], v[124:127]
	v_mfma_f32_16x16x32_bf16 v[120:123], v[136:139], v[182:185], v[120:123]
	v_mfma_f32_16x16x32_bf16 v[112:115], v[128:131], v[194:197], v[112:115]
	v_mfma_f32_16x16x32_bf16 v[104:107], v[136:139], v[194:197], v[104:107]
	v_mfma_f32_16x16x32_bf16 v[96:99], v[128:131], v[202:205], v[96:99]
	v_mfma_f32_16x16x32_bf16 v[88:91], v[136:139], v[202:205], v[88:91]
	v_mfma_f32_16x16x32_bf16 v[80:83], v[128:131], v[210:213], v[80:83]
	v_mfma_f32_16x16x32_bf16 v[72:75], v[136:139], v[210:213], v[72:75]
	v_mfma_f32_16x16x32_bf16 v[124:127], v[132:135], v[186:189], v[124:127]
	v_mfma_f32_16x16x32_bf16 v[120:123], v[140:143], v[186:189], v[120:123]
	v_mfma_f32_16x16x32_bf16 v[112:115], v[132:135], v[198:201], v[112:115]
	v_mfma_f32_16x16x32_bf16 v[104:107], v[140:143], v[198:201], v[104:107]
	v_mfma_f32_16x16x32_bf16 v[96:99], v[132:135], v[206:209], v[96:99]
	v_mfma_f32_16x16x32_bf16 v[88:91], v[140:143], v[206:209], v[88:91]
	v_mfma_f32_16x16x32_bf16 v[80:83], v[132:135], v[214:217], v[80:83]
	v_mfma_f32_16x16x32_bf16 v[72:75], v[140:143], v[214:217], v[72:75]
	s_setprio 0
	s_setprio 1
	v_mfma_f32_16x16x32_bf16 v[116:119], v[166:169], v[182:185], v[116:119]
	v_mfma_f32_16x16x32_bf16 v[108:111], v[174:177], v[182:185], v[108:111]
	v_mfma_f32_16x16x32_bf16 v[100:103], v[166:169], v[194:197], v[100:103]
	v_mfma_f32_16x16x32_bf16 v[92:95], v[174:177], v[194:197], v[92:95]
	v_mfma_f32_16x16x32_bf16 v[84:87], v[166:169], v[202:205], v[84:87]
	v_mfma_f32_16x16x32_bf16 v[76:79], v[174:177], v[202:205], v[76:79]
	v_mfma_f32_16x16x32_bf16 v[68:71], v[166:169], v[210:213], v[68:71]
	v_mfma_f32_16x16x32_bf16 v[64:67], v[174:177], v[210:213], v[64:67]
	v_mfma_f32_16x16x32_bf16 v[116:119], v[170:173], v[186:189], v[116:119]
	v_mfma_f32_16x16x32_bf16 v[108:111], v[178:181], v[186:189], v[108:111]
	v_mfma_f32_16x16x32_bf16 v[100:103], v[170:173], v[198:201], v[100:103]
	v_mfma_f32_16x16x32_bf16 v[92:95], v[178:181], v[198:201], v[92:95]
	v_mfma_f32_16x16x32_bf16 v[84:87], v[170:173], v[206:209], v[84:87]
	v_mfma_f32_16x16x32_bf16 v[76:79], v[178:181], v[206:209], v[76:79]
	v_mfma_f32_16x16x32_bf16 v[68:71], v[170:173], v[214:217], v[68:71]
	v_mfma_f32_16x16x32_bf16 v[64:67], v[178:181], v[214:217], v[64:67]
	s_setprio 0
	s_barrier
	s_add_i32 s11, s77, s63
	v_lshl_add_u64 v[190:191], s[58:59], 0, v[146:147]
	s_mov_b32 m0, s11
	ds_read_b128 v[182:185], v165 offset:16384
	ds_read_b128 v[186:189], v165 offset:17408
	ds_read_b128 v[194:197], v165 offset:18432
	ds_read_b128 v[198:201], v165 offset:19456
	ds_read_b128 v[202:205], v165 offset:20480
	ds_read_b128 v[206:209], v165 offset:21504
	ds_read_b128 v[210:213], v165 offset:22528
	ds_read_b128 v[214:217], v165 offset:23552
	global_load_lds_dwordx4 v[190:191], off
	s_add_i32 m0, s11, 0x2000
	s_add_u32 s78, s58, 0x40000
	v_lshl_add_u64 v[218:219], s[58:59], 0, v[150:151]
	s_addc_u32 s79, s59, 0
	s_add_i32 s10, s10, s63
	global_load_lds_dwordx4 v[218:219], off
	v_lshl_add_u64 v[220:221], s[78:79], 0, v[146:147]
	s_mov_b32 m0, s10
	v_lshl_add_u64 v[222:223], s[60:61], 0, v[148:149]
	global_load_lds_dwordx4 v[220:221], off
	v_lshl_add_u64 v[220:221], s[78:79], 0, v[150:151]
	s_add_i32 m0, s10, 0x2000
	s_nop 0
	global_load_lds_dwordx4 v[220:221], off
	v_lshl_add_u64 v[220:221], s[60:61], 0, v[144:145]
	s_mov_b32 m0, s64
	s_nop 0
	global_load_lds_dwordx4 v[220:221], off
	s_mov_b32 m0, s65
	s_nop 0
	global_load_lds_dwordx4 v[222:223], off
	s_waitcnt vmcnt(8)
	s_waitcnt lgkmcnt(0)
	s_barrier
; #define PG8_STAGE(bufoff, gbase, voff) do { _Pragma("unroll") for (int _i = 0; _i < 2; ++_i) \
;         __builtin_amdgcn_global_load_lds((const unsigned*)((const char*)(gbase) + (voff)[_i]), (PG8_LAS unsigned*)(lds + (bufoff) + ldsw + _i * 8192), 16, 0, 0); } while (0)
; #define PG8_LDA(dst, b, h) do { _Pragma("unroll") for (int m = 0; m < 4; ++m) _Pragma("unroll") for (int k = 0; k < 2; ++k) dst[m][k] = *(const PG8_LAS bf16x8*)(lds + PG8_SA(b, h) + aoff + m * 2048 + k * 1024); } while (0)
; #define PG8_LDB(dst, b, h) do { _Pragma("unroll") for (int n = 0; n < 2; ++n) _Pragma("unroll") for (int k = 0; k < 2; ++k) dst[n][k] = *(const PG8_LAS bf16x8*)(lds + PG8_SB(b, h) + boff + n * 2048 + k * 1024); } while (0)
; #define PG8_MMA(ai, bj, At, Bt) do { __builtin_amdgcn_s_setprio(1); _Pragma("unroll") for (int m = 0; m < 4; ++m) _Pragma("unroll") for (int n = 0; n < 2; ++n) _Pragma("unroll") for (int k = 0; k < 2; ++k) \
;         acc[ai][bj][m][n] = __builtin_amdgcn_mfma_f32_16x16x32_bf16(Bt[n][k], At[m][k], acc[ai][bj][m][n], 0, 0, 0); __builtin_amdgcn_s_setprio(0); } while (0)
; #define PG8_WAIT_V(n) asm volatile("s_waitcnt vmcnt(" #n ")" ::: "memory")
; #define PG8_WAIT_L(n) asm volatile("s_waitcnt lgkmcnt(" #n ")" ::: "memory")
; #define PG8_BAR __builtin_amdgcn_s_barrier()
; #define PG8_SCHED __builtin_amdgcn_sched_barrier(0)
; template <class Epi, class Sched, bool ALIGN_EPI = false, bool SP2 = false>
; __device__ __forceinline__ void gemm_phase(PG8_LAS unsigned char* lds, const Gemm g, const Sched& S, const Epi& E) {
;     ...
;             PG8_WAIT_V(8); PG8_WAIT_L(0); PG8_BAR; PG8_MMA(1, 0, At, B0); PG8_MMA(1, 1, At, B1); PG8_BAR; PG8_SCHED;
;             PG8_LDB(B0, 1, 0); PG8_LDB(B1, 1, 1); PG8_SCHED; PG8_LDA(At, 1, 0); PG8_STAGE(PG8_SA(0, 1), a2 + hstep, voffA);
;             PG8_WAIT_V(8); PG8_WAIT_L(0); PG8_BAR; PG8_MMA(0, 0, At, B0); PG8_MMA(0, 1, At, B1); PG8_BAR; PG8_SCHED;
	s_setprio 1
	s_waitcnt lgkmcnt(0)
	v_mfma_f32_16x16x32_bf16 v[60:63], v[128:131], v[182:185], v[60:63]
	v_mfma_f32_16x16x32_bf16 v[56:59], v[136:139], v[182:185], v[56:59]
	v_mfma_f32_16x16x32_bf16 v[48:51], v[128:131], v[194:197], v[48:51]
	v_mfma_f32_16x16x32_bf16 v[40:43], v[136:139], v[194:197], v[40:43]
	v_mfma_f32_16x16x32_bf16 v[32:35], v[128:131], v[202:205], v[32:35]
	v_mfma_f32_16x16x32_bf16 v[24:27], v[136:139], v[202:205], v[24:27]
	v_mfma_f32_16x16x32_bf16 v[16:19], v[128:131], v[210:213], v[16:19]
	v_mfma_f32_16x16x32_bf16 v[8:11], v[136:139], v[210:213], v[8:11]
	v_mfma_f32_16x16x32_bf16 v[60:63], v[132:135], v[186:189], v[60:63]
	v_mfma_f32_16x16x32_bf16 v[56:59], v[140:143], v[186:189], v[56:59]
	v_mfma_f32_16x16x32_bf16 v[48:51], v[132:135], v[198:201], v[48:51]
	v_mfma_f32_16x16x32_bf16 v[40:43], v[140:143], v[198:201], v[40:43]
	v_mfma_f32_16x16x32_bf16 v[32:35], v[132:135], v[206:209], v[32:35]
	v_mfma_f32_16x16x32_bf16 v[24:27], v[140:143], v[206:209], v[24:27]
	v_mfma_f32_16x16x32_bf16 v[16:19], v[132:135], v[214:217], v[16:19]
	v_mfma_f32_16x16x32_bf16 v[8:11], v[140:143], v[214:217], v[8:11]
	s_setprio 0
	s_setprio 1
	v_mfma_f32_16x16x32_bf16 v[52:55], v[166:169], v[182:185], v[52:55]
	v_mfma_f32_16x16x32_bf16 v[44:47], v[174:177], v[182:185], v[44:47]
	v_mfma_f32_16x16x32_bf16 v[36:39], v[166:169], v[194:197], v[36:39]
	v_mfma_f32_16x16x32_bf16 v[28:31], v[174:177], v[194:197], v[28:31]
	v_mfma_f32_16x16x32_bf16 v[20:23], v[166:169], v[202:205], v[20:23]
	v_mfma_f32_16x16x32_bf16 v[12:15], v[174:177], v[202:205], v[12:15]
	v_mfma_f32_16x16x32_bf16 v[4:7], v[166:169], v[210:213], v[4:7]
	v_mfma_f32_16x16x32_bf16 v[0:3], v[174:177], v[210:213], v[0:3]
	v_mfma_f32_16x16x32_bf16 v[52:55], v[170:173], v[186:189], v[52:55]
	v_mfma_f32_16x16x32_bf16 v[44:47], v[178:181], v[186:189], v[44:47]
	v_mfma_f32_16x16x32_bf16 v[36:39], v[170:173], v[198:201], v[36:39]
	v_mfma_f32_16x16x32_bf16 v[28:31], v[178:181], v[198:201], v[28:31]
	v_mfma_f32_16x16x32_bf16 v[20:23], v[170:173], v[206:209], v[20:23]
	v_mfma_f32_16x16x32_bf16 v[12:15], v[178:181], v[206:209], v[12:15]
	v_mfma_f32_16x16x32_bf16 v[4:7], v[170:173], v[214:217], v[4:7]
	v_mfma_f32_16x16x32_bf16 v[0:3], v[178:181], v[214:217], v[0:3]
	s_setprio 0
	s_barrier
	s_add_i32 s10, 0, 0x18000
	s_add_i32 s11, 0, 0x1c000
	v_add_u32_e32 v140, s10, v163
	v_add_u32_e32 v162, s11, v163
	ds_read_b128 v[128:131], v140
	ds_read_b128 v[132:135], v140 offset:1024
	ds_read_b128 v[136:139], v140 offset:2048
	ds_read_b128 v[140:143], v140 offset:3072
	ds_read_b128 v[166:169], v162
	ds_read_b128 v[170:173], v162 offset:1024
	ds_read_b128 v[174:177], v162 offset:2048
	ds_read_b128 v[178:181], v162 offset:3072
	s_add_u32 s60, s60, 0x40000
	s_addc_u32 s61, s61, 0
	s_mov_b32 m0, s66
	v_lshl_add_u64 v[224:225], s[60:61], 0, v[144:145]
	ds_read_b128 v[182:185], v165 offset:32768
	ds_read_b128 v[186:189], v165 offset:33792
	ds_read_b128 v[194:197], v165 offset:34816
	ds_read_b128 v[198:201], v165 offset:35840
	ds_read_b128 v[202:205], v165 offset:36864
	ds_read_b128 v[206:209], v165 offset:37888
	ds_read_b128 v[210:213], v165 offset:38912
	ds_read_b128 v[214:217], v165 offset:39936
	global_load_lds_dwordx4 v[224:225], off
	v_lshl_add_u64 v[224:225], s[60:61], 0, v[148:149]
	s_mov_b32 m0, s67
	s_nop 0
	global_load_lds_dwordx4 v[224:225], off
	s_waitcnt vmcnt(8)
	s_waitcnt lgkmcnt(0)
	s_barrier
	s_setprio 1
	s_waitcnt lgkmcnt(0)
	v_mfma_f32_16x16x32_bf16 v[124:127], v[128:131], v[182:185], v[124:127]
	v_mfma_f32_16x16x32_bf16 v[120:123], v[136:139], v[182:185], v[120:123]
	v_mfma_f32_16x16x32_bf16 v[112:115], v[128:131], v[194:197], v[112:115]
	v_mfma_f32_16x16x32_bf16 v[104:107], v[136:139], v[194:197], v[104:107]
	v_mfma_f32_16x16x32_bf16 v[96:99], v[128:131], v[202:205], v[96:99]
	v_mfma_f32_16x16x32_bf16 v[88:91], v[136:139], v[202:205], v[88:91]
	v_mfma_f32_16x16x32_bf16 v[80:83], v[128:131], v[210:213], v[80:83]
	v_mfma_f32_16x16x32_bf16 v[72:75], v[136:139], v[210:213], v[72:75]
	v_mfma_f32_16x16x32_bf16 v[124:127], v[132:135], v[186:189], v[124:127]
	v_mfma_f32_16x16x32_bf16 v[120:123], v[140:143], v[186:189], v[120:123]
	v_mfma_f32_16x16x32_bf16 v[112:115], v[132:135], v[198:201], v[112:115]
	v_mfma_f32_16x16x32_bf16 v[104:107], v[140:143], v[198:201], v[104:107]
	v_mfma_f32_16x16x32_bf16 v[96:99], v[132:135], v[206:209], v[96:99]
	v_mfma_f32_16x16x32_bf16 v[88:91], v[140:143], v[206:209], v[88:91]
	v_mfma_f32_16x16x32_bf16 v[80:83], v[132:135], v[214:217], v[80:83]
	v_mfma_f32_16x16x32_bf16 v[72:75], v[140:143], v[214:217], v[72:75]
	s_setprio 0
	s_setprio 1
	v_mfma_f32_16x16x32_bf16 v[116:119], v[166:169], v[182:185], v[116:119]
	v_mfma_f32_16x16x32_bf16 v[108:111], v[174:177], v[182:185], v[108:111]
	v_mfma_f32_16x16x32_bf16 v[100:103], v[166:169], v[194:197], v[100:103]
	v_mfma_f32_16x16x32_bf16 v[92:95], v[174:177], v[194:197], v[92:95]
	v_mfma_f32_16x16x32_bf16 v[84:87], v[166:169], v[202:205], v[84:87]
	v_mfma_f32_16x16x32_bf16 v[76:79], v[174:177], v[202:205], v[76:79]
	v_mfma_f32_16x16x32_bf16 v[68:71], v[166:169], v[210:213], v[68:71]
	v_mfma_f32_16x16x32_bf16 v[64:67], v[174:177], v[210:213], v[64:67]
	v_mfma_f32_16x16x32_bf16 v[116:119], v[170:173], v[186:189], v[116:119]
	v_mfma_f32_16x16x32_bf16 v[108:111], v[178:181], v[186:189], v[108:111]
	v_mfma_f32_16x16x32_bf16 v[100:103], v[170:173], v[198:201], v[100:103]
	v_mfma_f32_16x16x32_bf16 v[92:95], v[178:181], v[198:201], v[92:95]
	v_mfma_f32_16x16x32_bf16 v[84:87], v[170:173], v[206:209], v[84:87]
	v_mfma_f32_16x16x32_bf16 v[76:79], v[178:181], v[206:209], v[76:79]
	v_mfma_f32_16x16x32_bf16 v[68:71], v[170:173], v[214:217], v[68:71]
	v_mfma_f32_16x16x32_bf16 v[64:67], v[178:181], v[214:217], v[64:67]
	s_setprio 0
	s_barrier
; #define PG8_STAGE(bufoff, gbase, voff) do { _Pragma("unroll") for (int _i = 0; _i < 2; ++_i) \
;         __builtin_amdgcn_global_load_lds((const unsigned*)((const char*)(gbase) + (voff)[_i]), (PG8_LAS unsigned*)(lds + (bufoff) + ldsw + _i * 8192), 16, 0, 0); } while (0)
; #define PG8_LDA(dst, b, h) do { _Pragma("unroll") for (int m = 0; m < 4; ++m) _Pragma("unroll") for (int k = 0; k < 2; ++k) dst[m][k] = *(const PG8_LAS bf16x8*)(lds + PG8_SA(b, h) + aoff + m * 2048 + k * 1024); } while (0)
; #define PG8_LDB(dst, b, h) do { _Pragma("unroll") for (int n = 0; n < 2; ++n) _Pragma("unroll") for (int k = 0; k < 2; ++k) dst[n][k] = *(const PG8_LAS bf16x8*)(lds + PG8_SB(b, h) + boff + n * 2048 + k * 1024); } while (0)
; #define PG8_BAR __builtin_amdgcn_s_barrier()
; template <class Epi, class Sched, bool ALIGN_EPI = false, bool SP2 = false>
; __device__ __forceinline__ void gemm_phase(PG8_LAS unsigned char* lds, const Gemm g, const Sched& S, const Epi& E) {
;     ...
;             const bool last = (t == nt - 2);
;             const char* a1 = cA + (size_t)(t + 1) * kstep;
;             const char* a2 = last ? nA : cA + (size_t)(t + 2) * kstep; const char* b2 = last ? nB : cB + (size_t)(t + 2) * kstep;
;             const char* a3 = a2 + kstep; const char* b3 = b2 + kstep;
;             if (last && has_next) S.a_ready(nxt);
;             if constexpr (SP2) {
;             PG8_LDB(B0, 0, 0); PG8_LDB(B1, 0, 1); PG8_SCHED; PG8_LDA(At, 0, 0); PG8_STAGE(PG8_SA(1, 1), a1 + hstep, voffA);
;             PG8_WAIT_V(8); PG8_WAIT_L(0); PG8_BAR; PG8_MMA(0, 0, At, B0); PG8_MMA(0, 1, At, B1); PG8_BAR; PG8_SCHED;
;             PG8_LDA(At, 0, 1); PG8_STAGE(PG8_SB(0, 0), b2, voffB); PG8_STAGE(PG8_SB(0, 1), b2 + hstep, voffB); PG8_STAGE(PG8_SA(0, 0), a2, voffA);
;             PG8_WAIT_V(8); PG8_WAIT_L(0); PG8_BAR; PG8_MMA(1, 0, At, B0); PG8_MMA(1, 1, At, B1); PG8_BAR; PG8_SCHED;
;             PG8_LDB(B0, 1, 0); PG8_LDB(B1, 1, 1); PG8_SCHED; PG8_LDA(At, 1, 0); PG8_STAGE(PG8_SA(0, 1), a2 + hstep, voffA);
;             PG8_WAIT_V(8); PG8_WAIT_L(0); PG8_BAR; PG8_MMA(0, 0, At, B0); PG8_MMA(0, 1, At, B1); PG8_BAR; PG8_SCHED;
;             PG8_LDA(At, 1, 1); PG8_STAGE(PG8_SB(1, 0), b3, voffB); PG8_STAGE(PG8_SB(1, 1), b3 + hstep, voffB); PG8_STAGE(PG8_SA(1, 0), a3, voffA);
;             PG8_WAIT_V(8); PG8_WAIT_L(0); PG8_BAR; PG8_MMA(1, 0, At, B0); PG8_MMA(1, 1, At, B1); PG8_BAR; PG8_SCHED;
	s_add_i32 s10, s10, s63
	v_lshl_add_u64 v[190:191], v[190:191], 0, s[36:37]
	s_mov_b32 m0, s10
	ds_read_b128 v[182:185], v165 offset:49152
	ds_read_b128 v[186:189], v165 offset:50176
	ds_read_b128 v[194:197], v165 offset:51200
	ds_read_b128 v[198:201], v165 offset:52224
	ds_read_b128 v[202:205], v165 offset:53248
	ds_read_b128 v[206:209], v165 offset:54272
	ds_read_b128 v[210:213], v165 offset:55296
	ds_read_b128 v[214:217], v165 offset:56320
	global_load_lds_dwordx4 v[190:191], off
	s_add_i32 m0, s10, 0x2000
	s_add_u32 s58, s58, 0x40080
	v_lshl_add_u64 v[190:191], v[218:219], 0, s[36:37]
	s_addc_u32 s59, s59, 0
	s_add_i32 s10, s11, s63
	global_load_lds_dwordx4 v[190:191], off
	v_lshl_add_u64 v[190:191], s[58:59], 0, v[146:147]
	s_mov_b32 m0, s10
	s_nop 0
	global_load_lds_dwordx4 v[190:191], off
	v_lshl_add_u64 v[190:191], s[58:59], 0, v[150:151]
	s_add_i32 m0, s10, 0x2000
	s_nop 0
	global_load_lds_dwordx4 v[190:191], off
	v_lshl_add_u64 v[190:191], v[220:221], 0, s[36:37]
	s_mov_b32 m0, s70
	s_nop 0
	global_load_lds_dwordx4 v[190:191], off
	v_lshl_add_u64 v[190:191], v[222:223], 0, s[36:37]
	s_mov_b32 m0, s71
	s_nop 0
	global_load_lds_dwordx4 v[190:191], off
	s_waitcnt vmcnt(8)
	s_waitcnt lgkmcnt(0)
	s_barrier
	s_setprio 1
	s_waitcnt lgkmcnt(0)
	v_mfma_f32_16x16x32_bf16 v[60:63], v[128:131], v[182:185], v[60:63]
	v_mfma_f32_16x16x32_bf16 v[56:59], v[136:139], v[182:185], v[56:59]
	v_mfma_f32_16x16x32_bf16 v[48:51], v[128:131], v[194:197], v[48:51]
	v_mfma_f32_16x16x32_bf16 v[40:43], v[136:139], v[194:197], v[40:43]
	v_mfma_f32_16x16x32_bf16 v[32:35], v[128:131], v[202:205], v[32:35]
	v_mfma_f32_16x16x32_bf16 v[24:27], v[136:139], v[202:205], v[24:27]
	v_mfma_f32_16x16x32_bf16 v[16:19], v[128:131], v[210:213], v[16:19]
	v_mfma_f32_16x16x32_bf16 v[8:11], v[136:139], v[210:213], v[8:11]
	v_mfma_f32_16x16x32_bf16 v[60:63], v[132:135], v[186:189], v[60:63]
	v_mfma_f32_16x16x32_bf16 v[56:59], v[140:143], v[186:189], v[56:59]
	v_mfma_f32_16x16x32_bf16 v[48:51], v[132:135], v[198:201], v[48:51]
	v_mfma_f32_16x16x32_bf16 v[40:43], v[140:143], v[198:201], v[40:43]
	v_mfma_f32_16x16x32_bf16 v[32:35], v[132:135], v[206:209], v[32:35]
	v_mfma_f32_16x16x32_bf16 v[24:27], v[140:143], v[206:209], v[24:27]
	v_mfma_f32_16x16x32_bf16 v[16:19], v[132:135], v[214:217], v[16:19]
	v_mfma_f32_16x16x32_bf16 v[8:11], v[140:143], v[214:217], v[8:11]
	s_setprio 0
	s_setprio 1
	v_mfma_f32_16x16x32_bf16 v[52:55], v[166:169], v[182:185], v[52:55]
	v_mfma_f32_16x16x32_bf16 v[44:47], v[174:177], v[182:185], v[44:47]
	v_mfma_f32_16x16x32_bf16 v[36:39], v[166:169], v[194:197], v[36:39]
	v_mfma_f32_16x16x32_bf16 v[28:31], v[174:177], v[194:197], v[28:31]
	v_mfma_f32_16x16x32_bf16 v[20:23], v[166:169], v[202:205], v[20:23]
	v_mfma_f32_16x16x32_bf16 v[12:15], v[174:177], v[202:205], v[12:15]
	v_mfma_f32_16x16x32_bf16 v[4:7], v[166:169], v[210:213], v[4:7]
	v_mfma_f32_16x16x32_bf16 v[0:3], v[174:177], v[210:213], v[0:3]
	v_mfma_f32_16x16x32_bf16 v[52:55], v[170:173], v[186:189], v[52:55]
	v_mfma_f32_16x16x32_bf16 v[44:47], v[178:181], v[186:189], v[44:47]
	v_mfma_f32_16x16x32_bf16 v[36:39], v[170:173], v[198:201], v[36:39]
	v_mfma_f32_16x16x32_bf16 v[28:31], v[178:181], v[198:201], v[28:31]
	v_mfma_f32_16x16x32_bf16 v[20:23], v[170:173], v[206:209], v[20:23]
	v_mfma_f32_16x16x32_bf16 v[12:15], v[178:181], v[206:209], v[12:15]
	v_mfma_f32_16x16x32_bf16 v[4:7], v[170:173], v[214:217], v[4:7]
	v_mfma_f32_16x16x32_bf16 v[0:3], v[178:181], v[214:217], v[0:3]
	s_setprio 0
	s_add_i32 s76, s76, 2
	s_add_u32 s56, s56, 0x100
	s_addc_u32 s57, s57, 0
	s_add_u32 s49, s49, 0x100
	s_addc_u32 s51, s51, 0
	s_cmp_gt_u32 s76, 13
	s_cbranch_scc1 .Lrot_exit_g2
	s_add_u32 s10, s56, 0xfffc0080
	s_addc_u32 s11, s57, -1
	s_add_i32 s77, 0, 0x10000
	s_cmp_eq_u32 s76, 12
	s_cselect_b32 s61, s18, s11
	s_cselect_b32 s60, s19, s10
	s_cselect_b32 s59, s20, s51
	s_cselect_b32 s58, s43, s49
	s_add_i32 s10, 0, 0x14000
	s_barrier
	s_branch .Lrot_body_g2
.Lrot_exit_g2:
	s_barrier
	s_and_b64 vcc, exec, s[44:45]
	s_cbranch_vccz .LBB0_203
	s_barrier

; #define PG8_STAGE(bufoff, gbase, voff) do { _Pragma("unroll") for (int _i = 0; _i < 2; ++_i) \
;         __builtin_amdgcn_global_load_lds((const unsigned*)((const char*)(gbase) + (voff)[_i]), (PG8_LAS unsigned*)(lds + (bufoff) + ldsw + _i * 8192), 16, 0, 0); } while (0)
; #define PG8_LDA(dst, b, h) do { _Pragma("unroll") for (int m = 0; m < 4; ++m) _Pragma("unroll") for (int k = 0; k < 2; ++k) dst[m][k] = *(const PG8_LAS bf16x8*)(lds + PG8_SA(b, h) + aoff + m * 2048 + k * 1024); } while (0)
; #define PG8_LDB(dst, b, h) do { _Pragma("unroll") for (int n = 0; n < 2; ++n) _Pragma("unroll") for (int k = 0; k < 2; ++k) dst[n][k] = *(const PG8_LAS bf16x8*)(lds + PG8_SB(b, h) + boff + n * 2048 + k * 1024); } while (0)
; #define PG8_MMA(ai, bj, At, Bt) do { __builtin_amdgcn_s_setprio(1); _Pragma("unroll") for (int m = 0; m < 4; ++m) _Pragma("unroll") for (int n = 0; n < 2; ++n) _Pragma("unroll") for (int k = 0; k < 2; ++k) \
;         acc[ai][bj][m][n] = __builtin_amdgcn_mfma_f32_16x16x32_bf16(Bt[n][k], At[m][k], acc[ai][bj][m][n], 0, 0, 0); __builtin_amdgcn_s_setprio(0); } while (0)
; #define PG8_WAIT_V(n) asm volatile("s_waitcnt vmcnt(" #n ")" ::: "memory")
; #define PG8_WAIT_L(n) asm volatile("s_waitcnt lgkmcnt(" #n ")" ::: "memory")
; #define PG8_BAR __builtin_amdgcn_s_barrier()
; #define PG8_SCHED __builtin_amdgcn_sched_barrier(0)
; template <class Epi, class Sched, bool ALIGN_EPI = false, bool SP2 = false>
; __device__ __forceinline__ void gemm_phase(PG8_LAS unsigned char* lds, const Gemm g, const Sched& S, const Epi& E) {
;     ...
;             PG8_LDB(B0, 0, 0); PG8_LDB(B1, 0, 1); PG8_SCHED; PG8_LDA(At, 0, 0); PG8_STAGE(PG8_SA(1, 1), a1 + hstep, voffA);
;             PG8_WAIT_V(8); PG8_WAIT_L(0); PG8_BAR; PG8_MMA(0, 0, At, B0); PG8_MMA(0, 1, At, B1); PG8_BAR; PG8_SCHED;
;             PG8_LDA(At, 0, 1); PG8_STAGE(PG8_SB(0, 0), b2, voffB); PG8_STAGE(PG8_SB(0, 1), b2 + hstep, voffB); PG8_STAGE(PG8_SA(0, 0), a2, voffA);
.Lrot_body_g3:
	v_add_u32_e32 v140, s77, v246
	v_add_u32_e32 v156, s77, v246
	v_add_u32_e32 v156, 0x1000, v156
	ds_read_b128 v[128:131], v140
	ds_read_b128 v[132:135], v140 offset:1024
	ds_read_b128 v[136:139], v140 offset:2048
	ds_read_b128 v[140:143], v140 offset:3072
	ds_read_b128 v[144:147], v156
	ds_read_b128 v[148:151], v156 offset:1024
	ds_read_b128 v[152:155], v156 offset:2048
	ds_read_b128 v[156:159], v156 offset:3072
	v_lshl_add_u64 v[208:209], s[34:35], 0, v[204:205]
	s_add_i32 m0, s55, 0xc000
	ds_read_b128 v[160:163], v249
	ds_read_b128 v[164:167], v249 offset:1024
	ds_read_b128 v[168:171], v249 offset:2048
	ds_read_b128 v[172:175], v249 offset:3072
	ds_read_b128 v[176:179], v249 offset:4096
	ds_read_b128 v[180:183], v249 offset:5120
	ds_read_b128 v[184:187], v249 offset:6144
	ds_read_b128 v[188:191], v249 offset:7168
	global_load_lds_dwordx4 v[208:209], off
	v_lshl_add_u64 v[208:209], s[34:35], 0, v[206:207]
	s_add_i32 m0, s55, 0xe000
	s_nop 0
	global_load_lds_dwordx4 v[208:209], off
	s_waitcnt vmcnt(8)
	s_waitcnt lgkmcnt(0)
	s_barrier
	s_setprio 1
	s_waitcnt lgkmcnt(0)
	v_mfma_f32_16x16x32_bf16 v[124:127], v[128:131], v[160:163], v[124:127]
	v_mfma_f32_16x16x32_bf16 v[120:123], v[136:139], v[160:163], v[120:123]
	v_mfma_f32_16x16x32_bf16 v[116:119], v[128:131], v[168:171], v[116:119]
	v_mfma_f32_16x16x32_bf16 v[112:115], v[136:139], v[168:171], v[112:115]
	v_mfma_f32_16x16x32_bf16 v[108:111], v[128:131], v[176:179], v[108:111]
	v_mfma_f32_16x16x32_bf16 v[104:107], v[136:139], v[176:179], v[104:107]
	v_mfma_f32_16x16x32_bf16 v[100:103], v[128:131], v[184:187], v[100:103]
	v_mfma_f32_16x16x32_bf16 v[96:99], v[136:139], v[184:187], v[96:99]
	v_mfma_f32_16x16x32_bf16 v[124:127], v[132:135], v[164:167], v[124:127]
	v_mfma_f32_16x16x32_bf16 v[120:123], v[140:143], v[164:167], v[120:123]
	v_mfma_f32_16x16x32_bf16 v[116:119], v[132:135], v[172:175], v[116:119]
	v_mfma_f32_16x16x32_bf16 v[112:115], v[140:143], v[172:175], v[112:115]
	v_mfma_f32_16x16x32_bf16 v[108:111], v[132:135], v[180:183], v[108:111]
	v_mfma_f32_16x16x32_bf16 v[104:107], v[140:143], v[180:183], v[104:107]
	v_mfma_f32_16x16x32_bf16 v[100:103], v[132:135], v[188:191], v[100:103]
	v_mfma_f32_16x16x32_bf16 v[96:99], v[140:143], v[188:191], v[96:99]
	s_setprio 0
	s_setprio 1
	v_mfma_f32_16x16x32_bf16 v[92:95], v[144:147], v[160:163], v[92:95]
	v_mfma_f32_16x16x32_bf16 v[88:91], v[152:155], v[160:163], v[88:91]
	v_mfma_f32_16x16x32_bf16 v[84:87], v[144:147], v[168:171], v[84:87]
	v_mfma_f32_16x16x32_bf16 v[80:83], v[152:155], v[168:171], v[80:83]
	v_mfma_f32_16x16x32_bf16 v[76:79], v[144:147], v[176:179], v[76:79]
	v_mfma_f32_16x16x32_bf16 v[72:75], v[152:155], v[176:179], v[72:75]
	v_mfma_f32_16x16x32_bf16 v[68:71], v[144:147], v[184:187], v[68:71]
	v_mfma_f32_16x16x32_bf16 v[64:67], v[152:155], v[184:187], v[64:67]
	v_mfma_f32_16x16x32_bf16 v[92:95], v[148:151], v[164:167], v[92:95]
	v_mfma_f32_16x16x32_bf16 v[88:91], v[156:159], v[164:167], v[88:91]
	v_mfma_f32_16x16x32_bf16 v[84:87], v[148:151], v[172:175], v[84:87]
	v_mfma_f32_16x16x32_bf16 v[80:83], v[156:159], v[172:175], v[80:83]
	v_mfma_f32_16x16x32_bf16 v[76:79], v[148:151], v[180:183], v[76:79]
	v_mfma_f32_16x16x32_bf16 v[72:75], v[156:159], v[180:183], v[72:75]
	v_mfma_f32_16x16x32_bf16 v[68:71], v[148:151], v[188:191], v[68:71]
	v_mfma_f32_16x16x32_bf16 v[64:67], v[156:159], v[188:191], v[64:67]
	s_setprio 0
	s_barrier
	s_add_i32 s10, s77, s14
	v_lshl_add_u64 v[208:209], s[50:51], 0, v[198:199]
	s_mov_b32 m0, s10
	ds_read_b128 v[160:163], v249 offset:16384
	ds_read_b128 v[164:167], v249 offset:17408
	ds_read_b128 v[168:171], v249 offset:18432
	ds_read_b128 v[172:175], v249 offset:19456
	ds_read_b128 v[176:179], v249 offset:20480
	ds_read_b128 v[180:183], v249 offset:21504
	ds_read_b128 v[184:187], v249 offset:22528
	ds_read_b128 v[188:191], v249 offset:23552
	global_load_lds_dwordx4 v[208:209], off
	s_add_i32 m0, s10, 0x2000
	s_add_u32 s10, s50, 0x40000
	v_lshl_add_u64 v[210:211], s[50:51], 0, v[194:195]
	s_addc_u32 s11, s51, 0
	s_add_i32 s77, s78, s14
	global_load_lds_dwordx4 v[210:211], off
	v_lshl_add_u64 v[212:213], s[10:11], 0, v[198:199]
	s_mov_b32 m0, s77
	v_lshl_add_u64 v[214:215], s[52:53], 0, v[196:197]
	global_load_lds_dwordx4 v[212:213], off
	v_lshl_add_u64 v[212:213], s[10:11], 0, v[194:195]
	s_add_i32 m0, s77, 0x2000
	s_nop 0
	global_load_lds_dwordx4 v[212:213], off
	v_lshl_add_u64 v[212:213], s[52:53], 0, v[200:201]
	s_mov_b32 m0, s55
	s_nop 0
	global_load_lds_dwordx4 v[212:213], off
	s_mov_b32 m0, s58
	s_nop 0
	global_load_lds_dwordx4 v[214:215], off
	s_waitcnt vmcnt(8)
	s_waitcnt lgkmcnt(0)
	s_barrier
; #define PG8_STAGE(bufoff, gbase, voff) do { _Pragma("unroll") for (int _i = 0; _i < 2; ++_i) \
;         __builtin_amdgcn_global_load_lds((const unsigned*)((const char*)(gbase) + (voff)[_i]), (PG8_LAS unsigned*)(lds + (bufoff) + ldsw + _i * 8192), 16, 0, 0); } while (0)
; #define PG8_LDA(dst, b, h) do { _Pragma("unroll") for (int m = 0; m < 4; ++m) _Pragma("unroll") for (int k = 0; k < 2; ++k) dst[m][k] = *(const PG8_LAS bf16x8*)(lds + PG8_SA(b, h) + aoff + m * 2048 + k * 1024); } while (0)
; #define PG8_LDB(dst, b, h) do { _Pragma("unroll") for (int n = 0; n < 2; ++n) _Pragma("unroll") for (int k = 0; k < 2; ++k) dst[n][k] = *(const PG8_LAS bf16x8*)(lds + PG8_SB(b, h) + boff + n * 2048 + k * 1024); } while (0)
; #define PG8_MMA(ai, bj, At, Bt) do { __builtin_amdgcn_s_setprio(1); _Pragma("unroll") for (int m = 0; m < 4; ++m) _Pragma("unroll") for (int n = 0; n < 2; ++n) _Pragma("unroll") for (int k = 0; k < 2; ++k) \
;         acc[ai][bj][m][n] = __builtin_amdgcn_mfma_f32_16x16x32_bf16(Bt[n][k], At[m][k], acc[ai][bj][m][n], 0, 0, 0); __builtin_amdgcn_s_setprio(0); } while (0)
; #define PG8_WAIT_V(n) asm volatile("s_waitcnt vmcnt(" #n ")" ::: "memory")
; #define PG8_WAIT_L(n) asm volatile("s_waitcnt lgkmcnt(" #n ")" ::: "memory")
; #define PG8_BAR __builtin_amdgcn_s_barrier()
; #define PG8_SCHED __builtin_amdgcn_sched_barrier(0)
; template <class Epi, class Sched, bool ALIGN_EPI = false, bool SP2 = false>
; __device__ __forceinline__ void gemm_phase(PG8_LAS unsigned char* lds, const Gemm g, const Sched& S, const Epi& E) {
;     ...
;             PG8_WAIT_V(8); PG8_WAIT_L(0); PG8_BAR; PG8_MMA(1, 0, At, B0); PG8_MMA(1, 1, At, B1); PG8_BAR; PG8_SCHED;
;             PG8_LDB(B0, 1, 0); PG8_LDB(B1, 1, 1); PG8_SCHED; PG8_LDA(At, 1, 0); PG8_STAGE(PG8_SA(0, 1), a2 + hstep, voffA);
;             PG8_WAIT_V(8); PG8_WAIT_L(0); PG8_BAR; PG8_MMA(0, 0, At, B0); PG8_MMA(0, 1, At, B1); PG8_BAR; PG8_SCHED;
	s_setprio 1
	s_waitcnt lgkmcnt(0)
	v_mfma_f32_16x16x32_bf16 v[60:63], v[128:131], v[160:163], v[60:63]
	v_mfma_f32_16x16x32_bf16 v[56:59], v[136:139], v[160:163], v[56:59]
	v_mfma_f32_16x16x32_bf16 v[52:55], v[128:131], v[168:171], v[52:55]
	v_mfma_f32_16x16x32_bf16 v[48:51], v[136:139], v[168:171], v[48:51]
	v_mfma_f32_16x16x32_bf16 v[44:47], v[128:131], v[176:179], v[44:47]
	v_mfma_f32_16x16x32_bf16 v[40:43], v[136:139], v[176:179], v[40:43]
	v_mfma_f32_16x16x32_bf16 v[36:39], v[128:131], v[184:187], v[36:39]
	v_mfma_f32_16x16x32_bf16 v[32:35], v[136:139], v[184:187], v[32:35]
	v_mfma_f32_16x16x32_bf16 v[60:63], v[132:135], v[164:167], v[60:63]
	v_mfma_f32_16x16x32_bf16 v[56:59], v[140:143], v[164:167], v[56:59]
	v_mfma_f32_16x16x32_bf16 v[52:55], v[132:135], v[172:175], v[52:55]
	v_mfma_f32_16x16x32_bf16 v[48:51], v[140:143], v[172:175], v[48:51]
	v_mfma_f32_16x16x32_bf16 v[44:47], v[132:135], v[180:183], v[44:47]
	v_mfma_f32_16x16x32_bf16 v[40:43], v[140:143], v[180:183], v[40:43]
	v_mfma_f32_16x16x32_bf16 v[36:39], v[132:135], v[188:191], v[36:39]
	v_mfma_f32_16x16x32_bf16 v[32:35], v[140:143], v[188:191], v[32:35]
	s_setprio 0
	s_setprio 1
	v_mfma_f32_16x16x32_bf16 v[28:31], v[144:147], v[160:163], v[28:31]
	v_mfma_f32_16x16x32_bf16 v[24:27], v[152:155], v[160:163], v[24:27]
	v_mfma_f32_16x16x32_bf16 v[20:23], v[144:147], v[168:171], v[20:23]
	v_mfma_f32_16x16x32_bf16 v[16:19], v[152:155], v[168:171], v[16:19]
	v_mfma_f32_16x16x32_bf16 v[12:15], v[144:147], v[176:179], v[12:15]
	v_mfma_f32_16x16x32_bf16 v[8:11], v[152:155], v[176:179], v[8:11]
	v_mfma_f32_16x16x32_bf16 v[4:7], v[144:147], v[184:187], v[4:7]
	v_mfma_f32_16x16x32_bf16 v[0:3], v[152:155], v[184:187], v[0:3]
	v_mfma_f32_16x16x32_bf16 v[28:31], v[148:151], v[164:167], v[28:31]
	v_mfma_f32_16x16x32_bf16 v[24:27], v[156:159], v[164:167], v[24:27]
	v_mfma_f32_16x16x32_bf16 v[20:23], v[148:151], v[172:175], v[20:23]
	v_mfma_f32_16x16x32_bf16 v[16:19], v[156:159], v[172:175], v[16:19]
	v_mfma_f32_16x16x32_bf16 v[12:15], v[148:151], v[180:183], v[12:15]
	v_mfma_f32_16x16x32_bf16 v[8:11], v[156:159], v[180:183], v[8:11]
	v_mfma_f32_16x16x32_bf16 v[4:7], v[148:151], v[188:191], v[4:7]
	v_mfma_f32_16x16x32_bf16 v[0:3], v[156:159], v[188:191], v[0:3]
	s_setprio 0
	s_barrier
	s_add_i32 s77, 0, 0x18000
	s_add_i32 s78, 0, 0x1c000
	v_add_u32_e32 v140, s77, v246
	v_add_u32_e32 v156, s77, v246
	v_add_u32_e32 v156, 0x1000, v156
	ds_read_b128 v[128:131], v140
	ds_read_b128 v[132:135], v140 offset:1024
	ds_read_b128 v[136:139], v140 offset:2048
	ds_read_b128 v[140:143], v140 offset:3072
	ds_read_b128 v[144:147], v156
	ds_read_b128 v[148:151], v156 offset:1024
	ds_read_b128 v[152:155], v156 offset:2048
	ds_read_b128 v[156:159], v156 offset:3072
	s_add_u32 s10, s52, 0x40000
	s_addc_u32 s11, s53, 0
	s_mov_b32 m0, s59
	v_lshl_add_u64 v[216:217], s[10:11], 0, v[200:201]
	ds_read_b128 v[160:163], v249 offset:32768
	ds_read_b128 v[164:167], v249 offset:33792
	ds_read_b128 v[168:171], v249 offset:34816
	ds_read_b128 v[172:175], v249 offset:35840
	ds_read_b128 v[176:179], v249 offset:36864
	ds_read_b128 v[180:183], v249 offset:37888
	ds_read_b128 v[184:187], v249 offset:38912
	ds_read_b128 v[188:191], v249 offset:39936
	global_load_lds_dwordx4 v[216:217], off
	v_lshl_add_u64 v[216:217], s[10:11], 0, v[196:197]
	s_mov_b32 m0, s60
	s_nop 0
	global_load_lds_dwordx4 v[216:217], off
	s_waitcnt vmcnt(8)
	s_waitcnt lgkmcnt(0)
	s_barrier
	s_setprio 1
	s_waitcnt lgkmcnt(0)
	v_mfma_f32_16x16x32_bf16 v[124:127], v[128:131], v[160:163], v[124:127]
	v_mfma_f32_16x16x32_bf16 v[120:123], v[136:139], v[160:163], v[120:123]
	v_mfma_f32_16x16x32_bf16 v[116:119], v[128:131], v[168:171], v[116:119]
	v_mfma_f32_16x16x32_bf16 v[112:115], v[136:139], v[168:171], v[112:115]
	v_mfma_f32_16x16x32_bf16 v[108:111], v[128:131], v[176:179], v[108:111]
	v_mfma_f32_16x16x32_bf16 v[104:107], v[136:139], v[176:179], v[104:107]
	v_mfma_f32_16x16x32_bf16 v[100:103], v[128:131], v[184:187], v[100:103]
	v_mfma_f32_16x16x32_bf16 v[96:99], v[136:139], v[184:187], v[96:99]
	v_mfma_f32_16x16x32_bf16 v[124:127], v[132:135], v[164:167], v[124:127]
	v_mfma_f32_16x16x32_bf16 v[120:123], v[140:143], v[164:167], v[120:123]
	v_mfma_f32_16x16x32_bf16 v[116:119], v[132:135], v[172:175], v[116:119]
	v_mfma_f32_16x16x32_bf16 v[112:115], v[140:143], v[172:175], v[112:115]
	v_mfma_f32_16x16x32_bf16 v[108:111], v[132:135], v[180:183], v[108:111]
	v_mfma_f32_16x16x32_bf16 v[104:107], v[140:143], v[180:183], v[104:107]
	v_mfma_f32_16x16x32_bf16 v[100:103], v[132:135], v[188:191], v[100:103]
	v_mfma_f32_16x16x32_bf16 v[96:99], v[140:143], v[188:191], v[96:99]
	s_setprio 0
	s_setprio 1
	v_mfma_f32_16x16x32_bf16 v[92:95], v[144:147], v[160:163], v[92:95]
	v_mfma_f32_16x16x32_bf16 v[88:91], v[152:155], v[160:163], v[88:91]
	v_mfma_f32_16x16x32_bf16 v[84:87], v[144:147], v[168:171], v[84:87]
	v_mfma_f32_16x16x32_bf16 v[80:83], v[152:155], v[168:171], v[80:83]
	v_mfma_f32_16x16x32_bf16 v[76:79], v[144:147], v[176:179], v[76:79]
	v_mfma_f32_16x16x32_bf16 v[72:75], v[152:155], v[176:179], v[72:75]
	v_mfma_f32_16x16x32_bf16 v[68:71], v[144:147], v[184:187], v[68:71]
	v_mfma_f32_16x16x32_bf16 v[64:67], v[152:155], v[184:187], v[64:67]
	v_mfma_f32_16x16x32_bf16 v[92:95], v[148:151], v[164:167], v[92:95]
	v_mfma_f32_16x16x32_bf16 v[88:91], v[156:159], v[164:167], v[88:91]
	v_mfma_f32_16x16x32_bf16 v[84:87], v[148:151], v[172:175], v[84:87]
	v_mfma_f32_16x16x32_bf16 v[80:83], v[156:159], v[172:175], v[80:83]
	v_mfma_f32_16x16x32_bf16 v[76:79], v[148:151], v[180:183], v[76:79]
	v_mfma_f32_16x16x32_bf16 v[72:75], v[156:159], v[180:183], v[72:75]
	v_mfma_f32_16x16x32_bf16 v[68:71], v[148:151], v[188:191], v[68:71]
	v_mfma_f32_16x16x32_bf16 v[64:67], v[156:159], v[188:191], v[64:67]
	s_setprio 0
	s_barrier
; #define PG8_STAGE(bufoff, gbase, voff) do { _Pragma("unroll") for (int _i = 0; _i < 2; ++_i) \
;         __builtin_amdgcn_global_load_lds((const unsigned*)((const char*)(gbase) + (voff)[_i]), (PG8_LAS unsigned*)(lds + (bufoff) + ldsw + _i * 8192), 16, 0, 0); } while (0)
; #define PG8_LDA(dst, b, h) do { _Pragma("unroll") for (int m = 0; m < 4; ++m) _Pragma("unroll") for (int k = 0; k < 2; ++k) dst[m][k] = *(const PG8_LAS bf16x8*)(lds + PG8_SA(b, h) + aoff + m * 2048 + k * 1024); } while (0)
; #define PG8_LDB(dst, b, h) do { _Pragma("unroll") for (int n = 0; n < 2; ++n) _Pragma("unroll") for (int k = 0; k < 2; ++k) dst[n][k] = *(const PG8_LAS bf16x8*)(lds + PG8_SB(b, h) + boff + n * 2048 + k * 1024); } while (0)
; #define PG8_BAR __builtin_amdgcn_s_barrier()
; template <class Epi, class Sched, bool ALIGN_EPI = false, bool SP2 = false>
; __device__ __forceinline__ void gemm_phase(PG8_LAS unsigned char* lds, const Gemm g, const Sched& S, const Epi& E) {
;     ...
;             const bool last = (t == nt - 2);
;             const char* a1 = cA + (size_t)(t + 1) * kstep;
;             const char* a2 = last ? nA : cA + (size_t)(t + 2) * kstep; const char* b2 = last ? nB : cB + (size_t)(t + 2) * kstep;
;             const char* a3 = a2 + kstep; const char* b3 = b2 + kstep;
;             if (last && has_next) S.a_ready(nxt);
;             if constexpr (SP2) {
;             PG8_LDB(B0, 0, 0); PG8_LDB(B1, 0, 1); PG8_SCHED; PG8_LDA(At, 0, 0); PG8_STAGE(PG8_SA(1, 1), a1 + hstep, voffA);
;             PG8_WAIT_V(8); PG8_WAIT_L(0); PG8_BAR; PG8_MMA(0, 0, At, B0); PG8_MMA(0, 1, At, B1); PG8_BAR; PG8_SCHED;
;             PG8_LDA(At, 0, 1); PG8_STAGE(PG8_SB(0, 0), b2, voffB); PG8_STAGE(PG8_SB(0, 1), b2 + hstep, voffB); PG8_STAGE(PG8_SA(0, 0), a2, voffA);
;             PG8_WAIT_V(8); PG8_WAIT_L(0); PG8_BAR; PG8_MMA(1, 0, At, B0); PG8_MMA(1, 1, At, B1); PG8_BAR; PG8_SCHED;
;             PG8_LDB(B0, 1, 0); PG8_LDB(B1, 1, 1); PG8_SCHED; PG8_LDA(At, 1, 0); PG8_STAGE(PG8_SA(0, 1), a2 + hstep, voffA);
;             PG8_WAIT_V(8); PG8_WAIT_L(0); PG8_BAR; PG8_MMA(0, 0, At, B0); PG8_MMA(0, 1, At, B1); PG8_BAR; PG8_SCHED;
;             PG8_LDA(At, 1, 1); PG8_STAGE(PG8_SB(1, 0), b3, voffB); PG8_STAGE(PG8_SB(1, 1), b3 + hstep, voffB); PG8_STAGE(PG8_SA(1, 0), a3, voffA);
;             PG8_WAIT_V(8); PG8_WAIT_L(0); PG8_BAR; PG8_MMA(1, 0, At, B0); PG8_MMA(1, 1, At, B1); PG8_BAR; PG8_SCHED;
	s_add_i32 s10, s77, s14
	v_lshl_add_u64 v[208:209], v[208:209], 0, s[36:37]
	s_mov_b32 m0, s10
	ds_read_b128 v[160:163], v249 offset:49152
	ds_read_b128 v[164:167], v249 offset:50176
	ds_read_b128 v[168:171], v249 offset:51200
	ds_read_b128 v[172:175], v249 offset:52224
	ds_read_b128 v[176:179], v249 offset:53248
	ds_read_b128 v[180:183], v249 offset:54272
	ds_read_b128 v[184:187], v249 offset:55296
	ds_read_b128 v[188:191], v249 offset:56320
	global_load_lds_dwordx4 v[208:209], off
	s_add_i32 m0, s10, 0x2000
	s_add_u32 s10, s50, 0x40080
	v_lshl_add_u64 v[208:209], v[210:211], 0, s[36:37]
	s_addc_u32 s11, s51, 0
	s_add_i32 s50, s78, s14
	global_load_lds_dwordx4 v[208:209], off
	v_lshl_add_u64 v[208:209], s[10:11], 0, v[198:199]
	s_mov_b32 m0, s50
	s_nop 0
	global_load_lds_dwordx4 v[208:209], off
	v_lshl_add_u64 v[208:209], s[10:11], 0, v[194:195]
	s_add_i32 m0, s50, 0x2000
	s_nop 0
	global_load_lds_dwordx4 v[208:209], off
	v_lshl_add_u64 v[208:209], v[212:213], 0, s[36:37]
	s_mov_b32 m0, s65
	s_nop 0
	global_load_lds_dwordx4 v[208:209], off
	v_lshl_add_u64 v[208:209], v[214:215], 0, s[36:37]
	s_mov_b32 m0, s66
	s_nop 0
	global_load_lds_dwordx4 v[208:209], off
	s_waitcnt vmcnt(8)
	s_waitcnt lgkmcnt(0)
	s_barrier
	s_setprio 1
	s_waitcnt lgkmcnt(0)
	v_mfma_f32_16x16x32_bf16 v[60:63], v[128:131], v[160:163], v[60:63]
	v_mfma_f32_16x16x32_bf16 v[56:59], v[136:139], v[160:163], v[56:59]
	v_mfma_f32_16x16x32_bf16 v[52:55], v[128:131], v[168:171], v[52:55]
	v_mfma_f32_16x16x32_bf16 v[48:51], v[136:139], v[168:171], v[48:51]
	v_mfma_f32_16x16x32_bf16 v[44:47], v[128:131], v[176:179], v[44:47]
	v_mfma_f32_16x16x32_bf16 v[40:43], v[136:139], v[176:179], v[40:43]
	v_mfma_f32_16x16x32_bf16 v[36:39], v[128:131], v[184:187], v[36:39]
	v_mfma_f32_16x16x32_bf16 v[32:35], v[136:139], v[184:187], v[32:35]
	v_mfma_f32_16x16x32_bf16 v[60:63], v[132:135], v[164:167], v[60:63]
	v_mfma_f32_16x16x32_bf16 v[56:59], v[140:143], v[164:167], v[56:59]
	v_mfma_f32_16x16x32_bf16 v[52:55], v[132:135], v[172:175], v[52:55]
	v_mfma_f32_16x16x32_bf16 v[48:51], v[140:143], v[172:175], v[48:51]
	v_mfma_f32_16x16x32_bf16 v[44:47], v[132:135], v[180:183], v[44:47]
	v_mfma_f32_16x16x32_bf16 v[40:43], v[140:143], v[180:183], v[40:43]
	v_mfma_f32_16x16x32_bf16 v[36:39], v[132:135], v[188:191], v[36:39]
	v_mfma_f32_16x16x32_bf16 v[32:35], v[140:143], v[188:191], v[32:35]
	s_setprio 0
	s_setprio 1
	v_mfma_f32_16x16x32_bf16 v[28:31], v[144:147], v[160:163], v[28:31]
	v_mfma_f32_16x16x32_bf16 v[24:27], v[152:155], v[160:163], v[24:27]
	v_mfma_f32_16x16x32_bf16 v[20:23], v[144:147], v[168:171], v[20:23]
	v_mfma_f32_16x16x32_bf16 v[16:19], v[152:155], v[168:171], v[16:19]
	v_mfma_f32_16x16x32_bf16 v[12:15], v[144:147], v[176:179], v[12:15]
	v_mfma_f32_16x16x32_bf16 v[8:11], v[152:155], v[176:179], v[8:11]
	v_mfma_f32_16x16x32_bf16 v[4:7], v[144:147], v[184:187], v[4:7]
	v_mfma_f32_16x16x32_bf16 v[0:3], v[152:155], v[184:187], v[0:3]
	v_mfma_f32_16x16x32_bf16 v[28:31], v[148:151], v[164:167], v[28:31]
	v_mfma_f32_16x16x32_bf16 v[24:27], v[156:159], v[164:167], v[24:27]
	v_mfma_f32_16x16x32_bf16 v[20:23], v[148:151], v[172:175], v[20:23]
	v_mfma_f32_16x16x32_bf16 v[16:19], v[156:159], v[172:175], v[16:19]
	v_mfma_f32_16x16x32_bf16 v[12:15], v[148:151], v[180:183], v[12:15]
	v_mfma_f32_16x16x32_bf16 v[8:11], v[156:159], v[180:183], v[8:11]
	v_mfma_f32_16x16x32_bf16 v[4:7], v[148:151], v[188:191], v[4:7]
	v_mfma_f32_16x16x32_bf16 v[0:3], v[156:159], v[188:191], v[0:3]
	s_setprio 0
	s_add_i32 s76, s76, 2
	s_add_u32 s34, s34, 0x100
	s_addc_u32 s35, s35, 0
	s_add_u32 s19, s19, 0x100
	s_addc_u32 s75, s75, 0
	s_cmp_gt_u32 s76, 5
	s_cbranch_scc1 .Lrot_exit_g3
	s_add_u32 s10, s34, 0xfffc0080
	s_addc_u32 s11, s35, -1
	s_add_i32 s77, 0, 0x10000
	s_cmp_eq_u32 s76, 4
	s_cselect_b32 s53, s45, s11
	s_cselect_b32 s52, s44, s10
	s_cselect_b32 s51, s49, s75
	s_cselect_b32 s50, s48, s19
	s_add_i32 s78, 0, 0x14000
	s_barrier
	s_branch .Lrot_body_g3
.Lrot_exit_g3:
	s_barrier
	s_and_b64 vcc, exec, s[24:25]
	s_cbranch_vccz .LBB0_491
	s_barrier

; #define PG8_STAGE(bufoff, gbase, voff) do { _Pragma("unroll") for (int _i = 0; _i < 2; ++_i) \
;         __builtin_amdgcn_global_load_lds((const unsigned*)((const char*)(gbase) + (voff)[_i]), (PG8_LAS unsigned*)(lds + (bufoff) + ldsw + _i * 8192), 16, 0, 0); } while (0)
; #define PG8_LDA(dst, b, h) do { _Pragma("unroll") for (int m = 0; m < 4; ++m) _Pragma("unroll") for (int k = 0; k < 2; ++k) dst[m][k] = *(const PG8_LAS bf16x8*)(lds + PG8_SA(b, h) + aoff + m * 2048 + k * 1024); } while (0)
; #define PG8_LDB(dst, b, h) do { _Pragma("unroll") for (int n = 0; n < 2; ++n) _Pragma("unroll") for (int k = 0; k < 2; ++k) dst[n][k] = *(const PG8_LAS bf16x8*)(lds + PG8_SB(b, h) + boff + n * 2048 + k * 1024); } while (0)
; #define PG8_MMA(ai, bj, At, Bt) do { __builtin_amdgcn_s_setprio(1); _Pragma("unroll") for (int m = 0; m < 4; ++m) _Pragma("unroll") for (int n = 0; n < 2; ++n) _Pragma("unroll") for (int k = 0; k < 2; ++k) \
;         acc[ai][bj][m][n] = __builtin_amdgcn_mfma_f32_16x16x32_bf16(Bt[n][k], At[m][k], acc[ai][bj][m][n], 0, 0, 0); __builtin_amdgcn_s_setprio(0); } while (0)
; #define PG8_WAIT_V(n) asm volatile("s_waitcnt vmcnt(" #n ")" ::: "memory")
; #define PG8_WAIT_L(n) asm volatile("s_waitcnt lgkmcnt(" #n ")" ::: "memory")
; #define PG8_BAR __builtin_amdgcn_s_barrier()
; #define PG8_SCHED __builtin_amdgcn_sched_barrier(0)
; template <class Epi, class Sched, bool ALIGN_EPI = false, bool SP2 = false>
; __device__ __forceinline__ void gemm_phase(PG8_LAS unsigned char* lds, const Gemm g, const Sched& S, const Epi& E) {
;     ...
;             const bool last = (t == nt - 2);
;             const char* a1 = cA + (size_t)(t + 1) * kstep;
;             const char* a2 = last ? nA : cA + (size_t)(t + 2) * kstep; const char* b2 = last ? nB : cB + (size_t)(t + 2) * kstep;
;             const char* a3 = a2 + kstep; const char* b3 = b2 + kstep;
;             if (last && has_next) S.a_ready(nxt);
;             if constexpr (SP2) {
;             PG8_LDB(B0, 0, 0); PG8_LDB(B1, 0, 1); PG8_SCHED; PG8_LDA(At, 0, 0); PG8_STAGE(PG8_SA(1, 1), a1 + hstep, voffA);
;             PG8_WAIT_V(8); PG8_WAIT_L(0); PG8_BAR; PG8_MMA(0, 0, At, B0); PG8_MMA(0, 1, At, B1); PG8_BAR; PG8_SCHED;
;             PG8_LDA(At, 0, 1); PG8_STAGE(PG8_SB(0, 0), b2, voffB); PG8_STAGE(PG8_SB(0, 1), b2 + hstep, voffB); PG8_STAGE(PG8_SA(0, 0), a2, voffA);
.LBB0_577:
	s_add_u32 s10, s44, 0xfffc0080
	s_addc_u32 s11, s45, -1
	s_add_i32 s64, 0, 0x10000
	s_cmp_eq_u32 s63, 12
	s_cselect_b32 s49, s29, s11
	s_cselect_b32 s48, s43, s10
	s_cselect_b32 s47, s27, s62
	s_cselect_b32 s46, s60, s61
	s_add_i32 s65, 0, 0x14000
.Lrot_body_g4:
	v_add_u32_e32 v146, s64, v149
	ds_read_b128 v[128:131], v146
	ds_read_b128 v[154:157], v146 offset:1024
	ds_read_b128 v[158:161], v146 offset:2048
	ds_read_b128 v[162:165], v146 offset:3072
	v_add_u32_e32 v146, s65, v149
	ds_read_b128 v[166:169], v146
	ds_read_b128 v[170:173], v146 offset:1024
	ds_read_b128 v[174:177], v146 offset:2048
	ds_read_b128 v[178:181], v146 offset:3072
	v_lshl_add_u64 v[190:191], s[44:45], 0, v[142:143]
	s_add_i32 m0, s51, 0xc000
	ds_read_b128 v[182:185], v153
	ds_read_b128 v[186:189], v153 offset:1024
	ds_read_b128 v[194:197], v153 offset:2048
	ds_read_b128 v[198:201], v153 offset:3072
	ds_read_b128 v[202:205], v153 offset:4096
	ds_read_b128 v[206:209], v153 offset:5120
	ds_read_b128 v[210:213], v153 offset:6144
	ds_read_b128 v[214:217], v153 offset:7168
	global_load_lds_dwordx4 v[190:191], off
	v_lshl_add_u64 v[190:191], s[44:45], 0, v[144:145]
	s_add_i32 m0, s51, 0xe000
	s_nop 0
	global_load_lds_dwordx4 v[190:191], off
	s_waitcnt vmcnt(8)
	s_waitcnt lgkmcnt(0)
	s_barrier
	s_setprio 1
	s_waitcnt lgkmcnt(0)
	v_mfma_f32_16x16x32_bf16 v[124:127], v[128:131], v[182:185], v[124:127]
	v_mfma_f32_16x16x32_bf16 v[116:119], v[158:161], v[182:185], v[116:119]
	v_mfma_f32_16x16x32_bf16 v[108:111], v[128:131], v[194:197], v[108:111]
	v_mfma_f32_16x16x32_bf16 v[100:103], v[158:161], v[194:197], v[100:103]
	v_mfma_f32_16x16x32_bf16 v[92:95], v[128:131], v[202:205], v[92:95]
	v_mfma_f32_16x16x32_bf16 v[84:87], v[158:161], v[202:205], v[84:87]
	v_mfma_f32_16x16x32_bf16 v[76:79], v[128:131], v[210:213], v[76:79]
	v_mfma_f32_16x16x32_bf16 v[68:71], v[158:161], v[210:213], v[68:71]
	v_mfma_f32_16x16x32_bf16 v[124:127], v[154:157], v[186:189], v[124:127]
	v_mfma_f32_16x16x32_bf16 v[116:119], v[162:165], v[186:189], v[116:119]
	v_mfma_f32_16x16x32_bf16 v[108:111], v[154:157], v[198:201], v[108:111]
	v_mfma_f32_16x16x32_bf16 v[100:103], v[162:165], v[198:201], v[100:103]
	v_mfma_f32_16x16x32_bf16 v[92:95], v[154:157], v[206:209], v[92:95]
	v_mfma_f32_16x16x32_bf16 v[84:87], v[162:165], v[206:209], v[84:87]
	v_mfma_f32_16x16x32_bf16 v[76:79], v[154:157], v[214:217], v[76:79]
	v_mfma_f32_16x16x32_bf16 v[68:71], v[162:165], v[214:217], v[68:71]
	s_setprio 0
	s_setprio 1
	v_mfma_f32_16x16x32_bf16 v[120:123], v[166:169], v[182:185], v[120:123]
	v_mfma_f32_16x16x32_bf16 v[112:115], v[174:177], v[182:185], v[112:115]
	v_mfma_f32_16x16x32_bf16 v[104:107], v[166:169], v[194:197], v[104:107]
	v_mfma_f32_16x16x32_bf16 v[96:99], v[174:177], v[194:197], v[96:99]
	v_mfma_f32_16x16x32_bf16 v[88:91], v[166:169], v[202:205], v[88:91]
	v_mfma_f32_16x16x32_bf16 v[80:83], v[174:177], v[202:205], v[80:83]
	v_mfma_f32_16x16x32_bf16 v[72:75], v[166:169], v[210:213], v[72:75]
	v_mfma_f32_16x16x32_bf16 v[64:67], v[174:177], v[210:213], v[64:67]
	v_mfma_f32_16x16x32_bf16 v[120:123], v[170:173], v[186:189], v[120:123]
	v_mfma_f32_16x16x32_bf16 v[112:115], v[178:181], v[186:189], v[112:115]
	v_mfma_f32_16x16x32_bf16 v[104:107], v[170:173], v[198:201], v[104:107]
	v_mfma_f32_16x16x32_bf16 v[96:99], v[178:181], v[198:201], v[96:99]
	v_mfma_f32_16x16x32_bf16 v[88:91], v[170:173], v[206:209], v[88:91]
	v_mfma_f32_16x16x32_bf16 v[80:83], v[178:181], v[206:209], v[80:83]
	v_mfma_f32_16x16x32_bf16 v[72:75], v[170:173], v[214:217], v[72:75]
	v_mfma_f32_16x16x32_bf16 v[64:67], v[178:181], v[214:217], v[64:67]
	s_setprio 0
	s_barrier
	s_add_i32 s10, s64, s19
	v_lshl_add_u64 v[190:191], s[46:47], 0, v[136:137]
	s_mov_b32 m0, s10
	ds_read_b128 v[182:185], v153 offset:16384
	ds_read_b128 v[186:189], v153 offset:17408
	ds_read_b128 v[194:197], v153 offset:18432
	ds_read_b128 v[198:201], v153 offset:19456
	ds_read_b128 v[202:205], v153 offset:20480
	ds_read_b128 v[206:209], v153 offset:21504
	ds_read_b128 v[210:213], v153 offset:22528
	ds_read_b128 v[214:217], v153 offset:23552
	global_load_lds_dwordx4 v[190:191], off
	s_add_i32 m0, s10, 0x2000
	s_add_u32 s10, s46, 0x40000
	v_lshl_add_u64 v[218:219], s[46:47], 0, v[132:133]
	s_addc_u32 s11, s47, 0
	s_add_i32 s64, s65, s19
	global_load_lds_dwordx4 v[218:219], off
	v_lshl_add_u64 v[220:221], s[10:11], 0, v[136:137]
	s_mov_b32 m0, s64
	v_lshl_add_u64 v[222:223], s[48:49], 0, v[134:135]
	global_load_lds_dwordx4 v[220:221], off
	v_lshl_add_u64 v[220:221], s[10:11], 0, v[132:133]
	s_add_i32 m0, s64, 0x2000
	s_nop 0
	global_load_lds_dwordx4 v[220:221], off
	v_lshl_add_u64 v[220:221], s[48:49], 0, v[138:139]
	s_mov_b32 m0, s51
	s_nop 0
	global_load_lds_dwordx4 v[220:221], off
	s_mov_b32 m0, s52
	s_nop 0
	global_load_lds_dwordx4 v[222:223], off
	s_waitcnt vmcnt(8)
	s_waitcnt lgkmcnt(0)
	s_barrier
; #define PG8_STAGE(bufoff, gbase, voff) do { _Pragma("unroll") for (int _i = 0; _i < 2; ++_i) \
;         __builtin_amdgcn_global_load_lds((const unsigned*)((const char*)(gbase) + (voff)[_i]), (PG8_LAS unsigned*)(lds + (bufoff) + ldsw + _i * 8192), 16, 0, 0); } while (0)
; #define PG8_LDA(dst, b, h) do { _Pragma("unroll") for (int m = 0; m < 4; ++m) _Pragma("unroll") for (int k = 0; k < 2; ++k) dst[m][k] = *(const PG8_LAS bf16x8*)(lds + PG8_SA(b, h) + aoff + m * 2048 + k * 1024); } while (0)
; #define PG8_LDB(dst, b, h) do { _Pragma("unroll") for (int n = 0; n < 2; ++n) _Pragma("unroll") for (int k = 0; k < 2; ++k) dst[n][k] = *(const PG8_LAS bf16x8*)(lds + PG8_SB(b, h) + boff + n * 2048 + k * 1024); } while (0)
; #define PG8_MMA(ai, bj, At, Bt) do { __builtin_amdgcn_s_setprio(1); _Pragma("unroll") for (int m = 0; m < 4; ++m) _Pragma("unroll") for (int n = 0; n < 2; ++n) _Pragma("unroll") for (int k = 0; k < 2; ++k) \
;         acc[ai][bj][m][n] = __builtin_amdgcn_mfma_f32_16x16x32_bf16(Bt[n][k], At[m][k], acc[ai][bj][m][n], 0, 0, 0); __builtin_amdgcn_s_setprio(0); } while (0)
; #define PG8_WAIT_V(n) asm volatile("s_waitcnt vmcnt(" #n ")" ::: "memory")
; #define PG8_WAIT_L(n) asm volatile("s_waitcnt lgkmcnt(" #n ")" ::: "memory")
; #define PG8_BAR __builtin_amdgcn_s_barrier()
; #define PG8_SCHED __builtin_amdgcn_sched_barrier(0)
; template <class Epi, class Sched, bool ALIGN_EPI = false, bool SP2 = false>
; __device__ __forceinline__ void gemm_phase(PG8_LAS unsigned char* lds, const Gemm g, const Sched& S, const Epi& E) {
;     ...
;             PG8_WAIT_V(8); PG8_WAIT_L(0); PG8_BAR; PG8_MMA(1, 0, At, B0); PG8_MMA(1, 1, At, B1); PG8_BAR; PG8_SCHED;
;             PG8_LDB(B0, 1, 0); PG8_LDB(B1, 1, 1); PG8_SCHED; PG8_LDA(At, 1, 0); PG8_STAGE(PG8_SA(0, 1), a2 + hstep, voffA);
;             PG8_WAIT_V(8); PG8_WAIT_L(0); PG8_BAR; PG8_MMA(0, 0, At, B0); PG8_MMA(0, 1, At, B1); PG8_BAR; PG8_SCHED;
	s_setprio 1
	s_waitcnt lgkmcnt(0)
	v_mfma_f32_16x16x32_bf16 v[60:63], v[128:131], v[182:185], v[60:63]
	v_mfma_f32_16x16x32_bf16 v[52:55], v[158:161], v[182:185], v[52:55]
	v_mfma_f32_16x16x32_bf16 v[44:47], v[128:131], v[194:197], v[44:47]
	v_mfma_f32_16x16x32_bf16 v[36:39], v[158:161], v[194:197], v[36:39]
	v_mfma_f32_16x16x32_bf16 v[28:31], v[128:131], v[202:205], v[28:31]
	v_mfma_f32_16x16x32_bf16 v[20:23], v[158:161], v[202:205], v[20:23]
	v_mfma_f32_16x16x32_bf16 v[12:15], v[128:131], v[210:213], v[12:15]
	v_mfma_f32_16x16x32_bf16 v[4:7], v[158:161], v[210:213], v[4:7]
	v_mfma_f32_16x16x32_bf16 v[60:63], v[154:157], v[186:189], v[60:63]
	v_mfma_f32_16x16x32_bf16 v[52:55], v[162:165], v[186:189], v[52:55]
	v_mfma_f32_16x16x32_bf16 v[44:47], v[154:157], v[198:201], v[44:47]
	v_mfma_f32_16x16x32_bf16 v[36:39], v[162:165], v[198:201], v[36:39]
	v_mfma_f32_16x16x32_bf16 v[28:31], v[154:157], v[206:209], v[28:31]
	v_mfma_f32_16x16x32_bf16 v[20:23], v[162:165], v[206:209], v[20:23]
	v_mfma_f32_16x16x32_bf16 v[12:15], v[154:157], v[214:217], v[12:15]
	v_mfma_f32_16x16x32_bf16 v[4:7], v[162:165], v[214:217], v[4:7]
	s_setprio 0
	s_setprio 1
	v_mfma_f32_16x16x32_bf16 v[56:59], v[166:169], v[182:185], v[56:59]
	v_mfma_f32_16x16x32_bf16 v[48:51], v[174:177], v[182:185], v[48:51]
	v_mfma_f32_16x16x32_bf16 v[40:43], v[166:169], v[194:197], v[40:43]
	v_mfma_f32_16x16x32_bf16 v[32:35], v[174:177], v[194:197], v[32:35]
	v_mfma_f32_16x16x32_bf16 v[24:27], v[166:169], v[202:205], v[24:27]
	v_mfma_f32_16x16x32_bf16 v[16:19], v[174:177], v[202:205], v[16:19]
	v_mfma_f32_16x16x32_bf16 v[8:11], v[166:169], v[210:213], v[8:11]
	v_mfma_f32_16x16x32_bf16 v[0:3], v[174:177], v[210:213], v[0:3]
	v_mfma_f32_16x16x32_bf16 v[56:59], v[170:173], v[186:189], v[56:59]
	v_mfma_f32_16x16x32_bf16 v[48:51], v[178:181], v[186:189], v[48:51]
	v_mfma_f32_16x16x32_bf16 v[40:43], v[170:173], v[198:201], v[40:43]
	v_mfma_f32_16x16x32_bf16 v[32:35], v[178:181], v[198:201], v[32:35]
	v_mfma_f32_16x16x32_bf16 v[24:27], v[170:173], v[206:209], v[24:27]
	v_mfma_f32_16x16x32_bf16 v[16:19], v[178:181], v[206:209], v[16:19]
	v_mfma_f32_16x16x32_bf16 v[8:11], v[170:173], v[214:217], v[8:11]
	v_mfma_f32_16x16x32_bf16 v[0:3], v[178:181], v[214:217], v[0:3]
	s_setprio 0
	s_barrier
	s_add_i32 s64, 0, 0x18000
	v_add_u32_e32 v146, s64, v149
	s_add_i32 s65, 0, 0x1c000
	ds_read_b128 v[128:131], v146
	ds_read_b128 v[154:157], v146 offset:1024
	ds_read_b128 v[158:161], v146 offset:2048
	ds_read_b128 v[162:165], v146 offset:3072
	v_add_u32_e32 v146, s65, v149
	ds_read_b128 v[166:169], v146
	ds_read_b128 v[170:173], v146 offset:1024
	ds_read_b128 v[174:177], v146 offset:2048
	ds_read_b128 v[178:181], v146 offset:3072
	s_add_u32 s10, s48, 0x40000
	s_addc_u32 s11, s49, 0
	s_mov_b32 m0, s53
	v_lshl_add_u64 v[224:225], s[10:11], 0, v[138:139]
	ds_read_b128 v[182:185], v153 offset:32768
	ds_read_b128 v[186:189], v153 offset:33792
	ds_read_b128 v[194:197], v153 offset:34816
	ds_read_b128 v[198:201], v153 offset:35840
	ds_read_b128 v[202:205], v153 offset:36864
	ds_read_b128 v[206:209], v153 offset:37888
	ds_read_b128 v[210:213], v153 offset:38912
	ds_read_b128 v[214:217], v153 offset:39936
	global_load_lds_dwordx4 v[224:225], off
	v_lshl_add_u64 v[224:225], s[10:11], 0, v[134:135]
	s_mov_b32 m0, s54
	s_nop 0
	global_load_lds_dwordx4 v[224:225], off
	s_waitcnt vmcnt(8)
	s_waitcnt lgkmcnt(0)
	s_barrier
	s_setprio 1
	s_waitcnt lgkmcnt(0)
	v_mfma_f32_16x16x32_bf16 v[124:127], v[128:131], v[182:185], v[124:127]
	v_mfma_f32_16x16x32_bf16 v[116:119], v[158:161], v[182:185], v[116:119]
	v_mfma_f32_16x16x32_bf16 v[108:111], v[128:131], v[194:197], v[108:111]
	v_mfma_f32_16x16x32_bf16 v[100:103], v[158:161], v[194:197], v[100:103]
	v_mfma_f32_16x16x32_bf16 v[92:95], v[128:131], v[202:205], v[92:95]
	v_mfma_f32_16x16x32_bf16 v[84:87], v[158:161], v[202:205], v[84:87]
	v_mfma_f32_16x16x32_bf16 v[76:79], v[128:131], v[210:213], v[76:79]
	v_mfma_f32_16x16x32_bf16 v[68:71], v[158:161], v[210:213], v[68:71]
	v_mfma_f32_16x16x32_bf16 v[124:127], v[154:157], v[186:189], v[124:127]
	v_mfma_f32_16x16x32_bf16 v[116:119], v[162:165], v[186:189], v[116:119]
	v_mfma_f32_16x16x32_bf16 v[108:111], v[154:157], v[198:201], v[108:111]
	v_mfma_f32_16x16x32_bf16 v[100:103], v[162:165], v[198:201], v[100:103]
	v_mfma_f32_16x16x32_bf16 v[92:95], v[154:157], v[206:209], v[92:95]
	v_mfma_f32_16x16x32_bf16 v[84:87], v[162:165], v[206:209], v[84:87]
	v_mfma_f32_16x16x32_bf16 v[76:79], v[154:157], v[214:217], v[76:79]
	v_mfma_f32_16x16x32_bf16 v[68:71], v[162:165], v[214:217], v[68:71]
	s_setprio 0
	s_setprio 1
	v_mfma_f32_16x16x32_bf16 v[120:123], v[166:169], v[182:185], v[120:123]
	v_mfma_f32_16x16x32_bf16 v[112:115], v[174:177], v[182:185], v[112:115]
	v_mfma_f32_16x16x32_bf16 v[104:107], v[166:169], v[194:197], v[104:107]
	v_mfma_f32_16x16x32_bf16 v[96:99], v[174:177], v[194:197], v[96:99]
	v_mfma_f32_16x16x32_bf16 v[88:91], v[166:169], v[202:205], v[88:91]
	v_mfma_f32_16x16x32_bf16 v[80:83], v[174:177], v[202:205], v[80:83]
	v_mfma_f32_16x16x32_bf16 v[72:75], v[166:169], v[210:213], v[72:75]
	v_mfma_f32_16x16x32_bf16 v[64:67], v[174:177], v[210:213], v[64:67]
	v_mfma_f32_16x16x32_bf16 v[120:123], v[170:173], v[186:189], v[120:123]
	v_mfma_f32_16x16x32_bf16 v[112:115], v[178:181], v[186:189], v[112:115]
	v_mfma_f32_16x16x32_bf16 v[104:107], v[170:173], v[198:201], v[104:107]
	v_mfma_f32_16x16x32_bf16 v[96:99], v[178:181], v[198:201], v[96:99]
	v_mfma_f32_16x16x32_bf16 v[88:91], v[170:173], v[206:209], v[88:91]
	v_mfma_f32_16x16x32_bf16 v[80:83], v[178:181], v[206:209], v[80:83]
	v_mfma_f32_16x16x32_bf16 v[72:75], v[170:173], v[214:217], v[72:75]
	v_mfma_f32_16x16x32_bf16 v[64:67], v[178:181], v[214:217], v[64:67]
	s_setprio 0
	s_barrier
; #define PG8_STAGE(bufoff, gbase, voff) do { _Pragma("unroll") for (int _i = 0; _i < 2; ++_i) \
;         __builtin_amdgcn_global_load_lds((const unsigned*)((const char*)(gbase) + (voff)[_i]), (PG8_LAS unsigned*)(lds + (bufoff) + ldsw + _i * 8192), 16, 0, 0); } while (0)
; #define PG8_LDA(dst, b, h) do { _Pragma("unroll") for (int m = 0; m < 4; ++m) _Pragma("unroll") for (int k = 0; k < 2; ++k) dst[m][k] = *(const PG8_LAS bf16x8*)(lds + PG8_SA(b, h) + aoff + m * 2048 + k * 1024); } while (0)
; #define PG8_LDB(dst, b, h) do { _Pragma("unroll") for (int n = 0; n < 2; ++n) _Pragma("unroll") for (int k = 0; k < 2; ++k) dst[n][k] = *(const PG8_LAS bf16x8*)(lds + PG8_SB(b, h) + boff + n * 2048 + k * 1024); } while (0)
; #define PG8_BAR __builtin_amdgcn_s_barrier()
; template <class Epi, class Sched, bool ALIGN_EPI = false, bool SP2 = false>
; __device__ __forceinline__ void gemm_phase(PG8_LAS unsigned char* lds, const Gemm g, const Sched& S, const Epi& E) {
;     ...
;             const bool last = (t == nt - 2);
;             const char* a1 = cA + (size_t)(t + 1) * kstep;
;             const char* a2 = last ? nA : cA + (size_t)(t + 2) * kstep; const char* b2 = last ? nB : cB + (size_t)(t + 2) * kstep;
;             const char* a3 = a2 + kstep; const char* b3 = b2 + kstep;
;             if (last && has_next) S.a_ready(nxt);
;             if constexpr (SP2) {
;             PG8_LDB(B0, 0, 0); PG8_LDB(B1, 0, 1); PG8_SCHED; PG8_LDA(At, 0, 0); PG8_STAGE(PG8_SA(1, 1), a1 + hstep, voffA);
;             PG8_WAIT_V(8); PG8_WAIT_L(0); PG8_BAR; PG8_MMA(0, 0, At, B0); PG8_MMA(0, 1, At, B1); PG8_BAR; PG8_SCHED;
;             PG8_LDA(At, 0, 1); PG8_STAGE(PG8_SB(0, 0), b2, voffB); PG8_STAGE(PG8_SB(0, 1), b2 + hstep, voffB); PG8_STAGE(PG8_SA(0, 0), a2, voffA);
;             PG8_WAIT_V(8); PG8_WAIT_L(0); PG8_BAR; PG8_MMA(1, 0, At, B0); PG8_MMA(1, 1, At, B1); PG8_BAR; PG8_SCHED;
;             PG8_LDB(B0, 1, 0); PG8_LDB(B1, 1, 1); PG8_SCHED; PG8_LDA(At, 1, 0); PG8_STAGE(PG8_SA(0, 1), a2 + hstep, voffA);
;             PG8_WAIT_V(8); PG8_WAIT_L(0); PG8_BAR; PG8_MMA(0, 0, At, B0); PG8_MMA(0, 1, At, B1); PG8_BAR; PG8_SCHED;
;             PG8_LDA(At, 1, 1); PG8_STAGE(PG8_SB(1, 0), b3, voffB); PG8_STAGE(PG8_SB(1, 1), b3 + hstep, voffB); PG8_STAGE(PG8_SA(1, 0), a3, voffA);
;             PG8_WAIT_V(8); PG8_WAIT_L(0); PG8_BAR; PG8_MMA(1, 0, At, B0); PG8_MMA(1, 1, At, B1); PG8_BAR; PG8_SCHED;
	s_add_i32 s10, s64, s19
	v_lshl_add_u64 v[190:191], v[190:191], 0, s[36:37]
	s_mov_b32 m0, s10
	ds_read_b128 v[182:185], v153 offset:49152
	ds_read_b128 v[186:189], v153 offset:50176
	ds_read_b128 v[194:197], v153 offset:51200
	ds_read_b128 v[198:201], v153 offset:52224
	ds_read_b128 v[202:205], v153 offset:53248
	ds_read_b128 v[206:209], v153 offset:54272
	ds_read_b128 v[210:213], v153 offset:55296
	ds_read_b128 v[214:217], v153 offset:56320
	global_load_lds_dwordx4 v[190:191], off
	s_add_i32 m0, s10, 0x2000
	s_add_u32 s10, s46, 0x40080
	v_lshl_add_u64 v[190:191], v[218:219], 0, s[36:37]
	s_addc_u32 s11, s47, 0
	s_add_i32 s46, s65, s19
	global_load_lds_dwordx4 v[190:191], off
	v_lshl_add_u64 v[190:191], s[10:11], 0, v[136:137]
	s_mov_b32 m0, s46
	s_nop 0
	global_load_lds_dwordx4 v[190:191], off
	v_lshl_add_u64 v[190:191], s[10:11], 0, v[132:133]
	s_add_i32 m0, s46, 0x2000
	s_nop 0
	global_load_lds_dwordx4 v[190:191], off
	v_lshl_add_u64 v[190:191], v[220:221], 0, s[36:37]
	s_mov_b32 m0, s20
	s_nop 0
	global_load_lds_dwordx4 v[190:191], off
	v_lshl_add_u64 v[190:191], v[222:223], 0, s[36:37]
	s_mov_b32 m0, s55
	s_nop 0
	global_load_lds_dwordx4 v[190:191], off
	s_waitcnt vmcnt(8)
	s_waitcnt lgkmcnt(0)
	s_barrier
	s_setprio 1
	s_waitcnt lgkmcnt(0)
	v_mfma_f32_16x16x32_bf16 v[60:63], v[128:131], v[182:185], v[60:63]
	v_mfma_f32_16x16x32_bf16 v[52:55], v[158:161], v[182:185], v[52:55]
	v_mfma_f32_16x16x32_bf16 v[44:47], v[128:131], v[194:197], v[44:47]
	v_mfma_f32_16x16x32_bf16 v[36:39], v[158:161], v[194:197], v[36:39]
	v_mfma_f32_16x16x32_bf16 v[28:31], v[128:131], v[202:205], v[28:31]
	v_mfma_f32_16x16x32_bf16 v[20:23], v[158:161], v[202:205], v[20:23]
	v_mfma_f32_16x16x32_bf16 v[12:15], v[128:131], v[210:213], v[12:15]
	v_mfma_f32_16x16x32_bf16 v[4:7], v[158:161], v[210:213], v[4:7]
	v_mfma_f32_16x16x32_bf16 v[60:63], v[154:157], v[186:189], v[60:63]
	v_mfma_f32_16x16x32_bf16 v[52:55], v[162:165], v[186:189], v[52:55]
	v_mfma_f32_16x16x32_bf16 v[44:47], v[154:157], v[198:201], v[44:47]
	v_mfma_f32_16x16x32_bf16 v[36:39], v[162:165], v[198:201], v[36:39]
	v_mfma_f32_16x16x32_bf16 v[28:31], v[154:157], v[206:209], v[28:31]
	v_mfma_f32_16x16x32_bf16 v[20:23], v[162:165], v[206:209], v[20:23]
	v_mfma_f32_16x16x32_bf16 v[12:15], v[154:157], v[214:217], v[12:15]
	v_mfma_f32_16x16x32_bf16 v[4:7], v[162:165], v[214:217], v[4:7]
	s_setprio 0
	s_setprio 1
	v_mfma_f32_16x16x32_bf16 v[56:59], v[166:169], v[182:185], v[56:59]
	v_mfma_f32_16x16x32_bf16 v[48:51], v[174:177], v[182:185], v[48:51]
	v_mfma_f32_16x16x32_bf16 v[40:43], v[166:169], v[194:197], v[40:43]
	v_mfma_f32_16x16x32_bf16 v[32:35], v[174:177], v[194:197], v[32:35]
	v_mfma_f32_16x16x32_bf16 v[24:27], v[166:169], v[202:205], v[24:27]
	v_mfma_f32_16x16x32_bf16 v[16:19], v[174:177], v[202:205], v[16:19]
	v_mfma_f32_16x16x32_bf16 v[8:11], v[166:169], v[210:213], v[8:11]
	v_mfma_f32_16x16x32_bf16 v[0:3], v[174:177], v[210:213], v[0:3]
	v_mfma_f32_16x16x32_bf16 v[56:59], v[170:173], v[186:189], v[56:59]
	v_mfma_f32_16x16x32_bf16 v[48:51], v[178:181], v[186:189], v[48:51]
	v_mfma_f32_16x16x32_bf16 v[40:43], v[170:173], v[198:201], v[40:43]
	v_mfma_f32_16x16x32_bf16 v[32:35], v[178:181], v[198:201], v[32:35]
	v_mfma_f32_16x16x32_bf16 v[24:27], v[170:173], v[206:209], v[24:27]
	v_mfma_f32_16x16x32_bf16 v[16:19], v[178:181], v[206:209], v[16:19]
	v_mfma_f32_16x16x32_bf16 v[8:11], v[170:173], v[214:217], v[8:11]
	v_mfma_f32_16x16x32_bf16 v[0:3], v[178:181], v[214:217], v[0:3]
	s_setprio 0
	s_add_i32 s63, s63, 2
	s_add_u32 s44, s44, 0x100
	s_addc_u32 s45, s45, 0
	s_add_u32 s61, s61, 0x100
	s_addc_u32 s62, s62, 0
	s_cmp_gt_u32 s63, 13
	s_cbranch_scc1 .Lrot_exit_g4
	s_add_u32 s10, s44, 0xfffc0080
	s_addc_u32 s11, s45, -1
	s_add_i32 s64, 0, 0x10000
	s_cmp_eq_u32 s63, 12
	s_cselect_b32 s49, s29, s11
	s_cselect_b32 s48, s43, s10
	s_cselect_b32 s47, s27, s62
	s_cselect_b32 s46, s60, s61
	s_add_i32 s65, 0, 0x14000
	s_barrier
	s_branch .Lrot_body_g4
